# prologue adaLN GEMV: four 32-row blocks unrolled and double-buffered (next block's loads issued before the current block is consumed)
# speedup vs baseline: 1.0044x; 1.0044x over previous
.LBB0_1588:
	s_mul_hi_u32 s19, s12, s8
	s_mul_i32 s18, s12, s8
	v_lshl_add_u64 v[224:225], s[18:19], 2, v[48:49]
	global_load_dword v112, v[224:225], off
	s_add_u32 s18, s18, s12
	s_addc_u32 s19, s19, 0
	v_lshl_add_u64 v[224:225], s[18:19], 2, v[48:49]
	global_load_dword v113, v[224:225], off
	s_add_u32 s18, s18, s12
	s_addc_u32 s19, s19, 0
	v_lshl_add_u64 v[224:225], s[18:19], 2, v[48:49]
	global_load_dword v114, v[224:225], off
	s_add_u32 s18, s18, s12
	s_addc_u32 s19, s19, 0
	v_lshl_add_u64 v[224:225], s[18:19], 2, v[48:49]
	global_load_dword v115, v[224:225], off
	s_add_u32 s18, s18, s12
	s_addc_u32 s19, s19, 0
	v_lshl_add_u64 v[224:225], s[18:19], 2, v[48:49]
	global_load_dword v116, v[224:225], off
	s_add_u32 s18, s18, s12
	s_addc_u32 s19, s19, 0
	v_lshl_add_u64 v[224:225], s[18:19], 2, v[48:49]
	global_load_dword v117, v[224:225], off
	s_add_u32 s18, s18, s12
	s_addc_u32 s19, s19, 0
	v_lshl_add_u64 v[224:225], s[18:19], 2, v[48:49]
	global_load_dword v118, v[224:225], off
	s_add_u32 s18, s18, s12
	s_addc_u32 s19, s19, 0
	v_lshl_add_u64 v[224:225], s[18:19], 2, v[48:49]
	global_load_dword v119, v[224:225], off
	s_add_u32 s18, s18, s12
	s_addc_u32 s19, s19, 0
	v_lshl_add_u64 v[224:225], s[18:19], 2, v[48:49]
	global_load_dword v120, v[224:225], off
	s_add_u32 s18, s18, s12
	s_addc_u32 s19, s19, 0
	v_lshl_add_u64 v[224:225], s[18:19], 2, v[48:49]
	global_load_dword v121, v[224:225], off
	s_add_u32 s18, s18, s12
	s_addc_u32 s19, s19, 0
	v_lshl_add_u64 v[224:225], s[18:19], 2, v[48:49]
	global_load_dword v122, v[224:225], off
	s_add_u32 s18, s18, s12
	s_addc_u32 s19, s19, 0
	v_lshl_add_u64 v[224:225], s[18:19], 2, v[48:49]
	global_load_dword v123, v[224:225], off
	s_add_u32 s18, s18, s12
	s_addc_u32 s19, s19, 0
	v_lshl_add_u64 v[224:225], s[18:19], 2, v[48:49]
	global_load_dword v124, v[224:225], off
	s_add_u32 s18, s18, s12
	s_addc_u32 s19, s19, 0
	v_lshl_add_u64 v[224:225], s[18:19], 2, v[48:49]
	global_load_dword v125, v[224:225], off
	s_add_u32 s18, s18, s12
	s_addc_u32 s19, s19, 0
	v_lshl_add_u64 v[224:225], s[18:19], 2, v[48:49]
	global_load_dword v126, v[224:225], off
	s_add_u32 s18, s18, s12
	s_addc_u32 s19, s19, 0
	v_lshl_add_u64 v[224:225], s[18:19], 2, v[48:49]
	global_load_dword v127, v[224:225], off
	s_add_u32 s18, s18, s12
	s_addc_u32 s19, s19, 0
	v_lshl_add_u64 v[224:225], s[18:19], 2, v[48:49]
	global_load_dword v128, v[224:225], off
	s_add_u32 s18, s18, s12
	s_addc_u32 s19, s19, 0
	v_lshl_add_u64 v[224:225], s[18:19], 2, v[48:49]
	global_load_dword v129, v[224:225], off
	s_add_u32 s18, s18, s12
	s_addc_u32 s19, s19, 0
	v_lshl_add_u64 v[224:225], s[18:19], 2, v[48:49]
	global_load_dword v130, v[224:225], off
	s_add_u32 s18, s18, s12
	s_addc_u32 s19, s19, 0
	v_lshl_add_u64 v[224:225], s[18:19], 2, v[48:49]
	global_load_dword v131, v[224:225], off
	s_add_u32 s18, s18, s12
	s_addc_u32 s19, s19, 0
	v_lshl_add_u64 v[224:225], s[18:19], 2, v[48:49]
	global_load_dword v132, v[224:225], off
	s_add_u32 s18, s18, s12
	s_addc_u32 s19, s19, 0
	v_lshl_add_u64 v[224:225], s[18:19], 2, v[48:49]
	global_load_dword v133, v[224:225], off
	s_add_u32 s18, s18, s12
	s_addc_u32 s19, s19, 0
	v_lshl_add_u64 v[224:225], s[18:19], 2, v[48:49]
	global_load_dword v134, v[224:225], off
	s_add_u32 s18, s18, s12
	s_addc_u32 s19, s19, 0
	v_lshl_add_u64 v[224:225], s[18:19], 2, v[48:49]
	global_load_dword v135, v[224:225], off
	s_add_u32 s18, s18, s12
	s_addc_u32 s19, s19, 0
	v_lshl_add_u64 v[224:225], s[18:19], 2, v[48:49]
	global_load_dword v136, v[224:225], off
	s_add_u32 s18, s18, s12
	s_addc_u32 s19, s19, 0
	v_lshl_add_u64 v[224:225], s[18:19], 2, v[48:49]
	global_load_dword v137, v[224:225], off
	s_add_u32 s18, s18, s12
	s_addc_u32 s19, s19, 0
	v_lshl_add_u64 v[224:225], s[18:19], 2, v[48:49]
	global_load_dword v138, v[224:225], off
	s_add_u32 s18, s18, s12
	s_addc_u32 s19, s19, 0
	v_lshl_add_u64 v[224:225], s[18:19], 2, v[48:49]
	global_load_dword v139, v[224:225], off
	s_add_u32 s18, s18, s12
	s_addc_u32 s19, s19, 0
	v_lshl_add_u64 v[224:225], s[18:19], 2, v[48:49]
	global_load_dword v140, v[224:225], off
	s_add_u32 s18, s18, s12
	s_addc_u32 s19, s19, 0
	v_lshl_add_u64 v[224:225], s[18:19], 2, v[48:49]
	global_load_dword v141, v[224:225], off
	s_add_u32 s18, s18, s12
	s_addc_u32 s19, s19, 0
	v_lshl_add_u64 v[224:225], s[18:19], 2, v[48:49]
	global_load_dword v142, v[224:225], off
	s_add_u32 s18, s18, s12
	s_addc_u32 s19, s19, 0
	v_lshl_add_u64 v[224:225], s[18:19], 2, v[48:49]
	global_load_dword v143, v[224:225], off
	s_add_u32 s18, s18, s12
	s_addc_u32 s19, s19, 0
	s_waitcnt vmcnt(31)
	v_lshl_add_u64 v[224:225], s[18:19], 2, v[48:49]
	global_load_dword v82, v[224:225], off
	s_add_u32 s18, s18, s12
	s_addc_u32 s19, s19, 0
	v_lshl_add_u64 v[224:225], s[18:19], 2, v[48:49]
	global_load_dword v83, v[224:225], off
	s_add_u32 s18, s18, s12
	s_addc_u32 s19, s19, 0
	v_lshl_add_u64 v[224:225], s[18:19], 2, v[48:49]
	global_load_dword v84, v[224:225], off
	s_add_u32 s18, s18, s12
	s_addc_u32 s19, s19, 0
	v_lshl_add_u64 v[224:225], s[18:19], 2, v[48:49]
	global_load_dword v85, v[224:225], off
	s_add_u32 s18, s18, s12
	s_addc_u32 s19, s19, 0
	v_lshl_add_u64 v[224:225], s[18:19], 2, v[48:49]
	global_load_dword v86, v[224:225], off
	s_add_u32 s18, s18, s12
	s_addc_u32 s19, s19, 0
	v_lshl_add_u64 v[224:225], s[18:19], 2, v[48:49]
	global_load_dword v87, v[224:225], off
	s_add_u32 s18, s18, s12
	s_addc_u32 s19, s19, 0
	v_lshl_add_u64 v[224:225], s[18:19], 2, v[48:49]
	global_load_dword v88, v[224:225], off
	s_add_u32 s18, s18, s12
	s_addc_u32 s19, s19, 0
	v_lshl_add_u64 v[224:225], s[18:19], 2, v[48:49]
	global_load_dword v89, v[224:225], off
	s_add_u32 s18, s18, s12
	s_addc_u32 s19, s19, 0
	v_lshl_add_u64 v[224:225], s[18:19], 2, v[48:49]
	global_load_dword v90, v[224:225], off
	s_add_u32 s18, s18, s12
	s_addc_u32 s19, s19, 0
	v_lshl_add_u64 v[224:225], s[18:19], 2, v[48:49]
	global_load_dword v91, v[224:225], off
	s_add_u32 s18, s18, s12
	s_addc_u32 s19, s19, 0
	v_lshl_add_u64 v[224:225], s[18:19], 2, v[48:49]
	global_load_dword v92, v[224:225], off
	s_add_u32 s18, s18, s12
	s_addc_u32 s19, s19, 0
	v_lshl_add_u64 v[224:225], s[18:19], 2, v[48:49]
	global_load_dword v93, v[224:225], off
	s_add_u32 s18, s18, s12
	s_addc_u32 s19, s19, 0
	v_lshl_add_u64 v[224:225], s[18:19], 2, v[48:49]
	global_load_dword v94, v[224:225], off
	s_add_u32 s18, s18, s12
	s_addc_u32 s19, s19, 0
	v_lshl_add_u64 v[224:225], s[18:19], 2, v[48:49]
	global_load_dword v95, v[224:225], off
	s_add_u32 s18, s18, s12
	s_addc_u32 s19, s19, 0
	v_lshl_add_u64 v[224:225], s[18:19], 2, v[48:49]
	global_load_dword v96, v[224:225], off
	s_add_u32 s18, s18, s12
	s_addc_u32 s19, s19, 0
	v_lshl_add_u64 v[224:225], s[18:19], 2, v[48:49]
	global_load_dword v97, v[224:225], off
	s_add_u32 s18, s18, s12
	s_addc_u32 s19, s19, 0
	v_lshl_add_u64 v[224:225], s[18:19], 2, v[48:49]
	global_load_dword v98, v[224:225], off
	s_add_u32 s18, s18, s12
	s_addc_u32 s19, s19, 0
	v_lshl_add_u64 v[224:225], s[18:19], 2, v[48:49]
	global_load_dword v99, v[224:225], off
	s_add_u32 s18, s18, s12
	s_addc_u32 s19, s19, 0
	v_lshl_add_u64 v[224:225], s[18:19], 2, v[48:49]
	global_load_dword v100, v[224:225], off
	s_add_u32 s18, s18, s12
	s_addc_u32 s19, s19, 0
	v_lshl_add_u64 v[224:225], s[18:19], 2, v[48:49]
	global_load_dword v101, v[224:225], off
	s_add_u32 s18, s18, s12
	s_addc_u32 s19, s19, 0
	v_lshl_add_u64 v[224:225], s[18:19], 2, v[48:49]
	global_load_dword v102, v[224:225], off
	s_add_u32 s18, s18, s12
	s_addc_u32 s19, s19, 0
	v_lshl_add_u64 v[224:225], s[18:19], 2, v[48:49]
	global_load_dword v103, v[224:225], off
	s_add_u32 s18, s18, s12
	s_addc_u32 s19, s19, 0
	v_lshl_add_u64 v[224:225], s[18:19], 2, v[48:49]
	global_load_dword v104, v[224:225], off
	s_add_u32 s18, s18, s12
	s_addc_u32 s19, s19, 0
	v_lshl_add_u64 v[224:225], s[18:19], 2, v[48:49]
	global_load_dword v105, v[224:225], off
	s_add_u32 s18, s18, s12
	s_addc_u32 s19, s19, 0
	v_lshl_add_u64 v[224:225], s[18:19], 2, v[48:49]
	global_load_dword v106, v[224:225], off
	s_add_u32 s18, s18, s12
	s_addc_u32 s19, s19, 0
	v_lshl_add_u64 v[224:225], s[18:19], 2, v[48:49]
	global_load_dword v107, v[224:225], off
	s_add_u32 s18, s18, s12
	s_addc_u32 s19, s19, 0
	v_lshl_add_u64 v[224:225], s[18:19], 2, v[48:49]
	global_load_dword v108, v[224:225], off
	s_add_u32 s18, s18, s12
	s_addc_u32 s19, s19, 0
	v_lshl_add_u64 v[224:225], s[18:19], 2, v[48:49]
	global_load_dword v109, v[224:225], off
	s_add_u32 s18, s18, s12
	s_addc_u32 s19, s19, 0
	v_lshl_add_u64 v[224:225], s[18:19], 2, v[48:49]
	global_load_dword v110, v[224:225], off
	s_add_u32 s18, s18, s12
	s_addc_u32 s19, s19, 0
	v_lshl_add_u64 v[224:225], s[18:19], 2, v[48:49]
	global_load_dword v111, v[224:225], off
	s_add_u32 s18, s18, s12
	s_addc_u32 s19, s19, 0
	v_lshl_add_u64 v[224:225], s[18:19], 2, v[48:49]
	global_load_dword v144, v[224:225], off
	s_add_u32 s18, s18, s12
	s_addc_u32 s19, s19, 0
	v_lshl_add_u64 v[224:225], s[18:19], 2, v[48:49]
	global_load_dword v145, v[224:225], off
	s_add_u32 s18, s18, s12
	s_addc_u32 s19, s19, 0
	s_lshl_b32 s9, s8, 2
	s_add_i32 s9, s15, s9
	v_mov_b32_e32 v226, s9
	ds_read_b128 v[192:195], v226
	ds_read_b128 v[196:199], v226 offset:16
	ds_read_b128 v[200:203], v226 offset:32
	ds_read_b128 v[204:207], v226 offset:48
	ds_read_b128 v[208:211], v226 offset:64
	ds_read_b128 v[212:215], v226 offset:80
	ds_read_b128 v[216:219], v226 offset:96
	ds_read_b128 v[220:223], v226 offset:112
	s_waitcnt lgkmcnt(0)
	s_waitcnt vmcnt(63)
	v_fmac_f32_e32 v26, v192, v112
	s_waitcnt vmcnt(62)
	v_fmac_f32_e32 v26, v193, v113
	s_waitcnt vmcnt(61)
	v_fmac_f32_e32 v26, v194, v114
	s_waitcnt vmcnt(60)
	v_fmac_f32_e32 v26, v195, v115
	s_waitcnt vmcnt(59)
	v_fmac_f32_e32 v26, v196, v116
	s_waitcnt vmcnt(58)
	v_fmac_f32_e32 v26, v197, v117
	s_waitcnt vmcnt(57)
	v_fmac_f32_e32 v26, v198, v118
	s_waitcnt vmcnt(56)
	v_fmac_f32_e32 v26, v199, v119
	s_waitcnt vmcnt(55)
	v_fmac_f32_e32 v26, v200, v120
	s_waitcnt vmcnt(54)
	v_fmac_f32_e32 v26, v201, v121
	s_waitcnt vmcnt(53)
	v_fmac_f32_e32 v26, v202, v122
	s_waitcnt vmcnt(52)
	v_fmac_f32_e32 v26, v203, v123
	s_waitcnt vmcnt(51)
	v_fmac_f32_e32 v26, v204, v124
	s_waitcnt vmcnt(50)
	v_fmac_f32_e32 v26, v205, v125
	s_waitcnt vmcnt(49)
	v_fmac_f32_e32 v26, v206, v126
	s_waitcnt vmcnt(48)
	v_fmac_f32_e32 v26, v207, v127
	s_waitcnt vmcnt(47)
	v_fmac_f32_e32 v26, v208, v128
	s_waitcnt vmcnt(46)
	v_fmac_f32_e32 v26, v209, v129
	s_waitcnt vmcnt(45)
	v_fmac_f32_e32 v26, v210, v130
	s_waitcnt vmcnt(44)
	v_fmac_f32_e32 v26, v211, v131
	s_waitcnt vmcnt(43)
	v_fmac_f32_e32 v26, v212, v132
	s_waitcnt vmcnt(42)
	v_fmac_f32_e32 v26, v213, v133
	s_waitcnt vmcnt(41)
	v_fmac_f32_e32 v26, v214, v134
	s_waitcnt vmcnt(40)
	v_fmac_f32_e32 v26, v215, v135
	s_waitcnt vmcnt(39)
	v_fmac_f32_e32 v26, v216, v136
	s_waitcnt vmcnt(38)
	v_fmac_f32_e32 v26, v217, v137
	s_waitcnt vmcnt(37)
	v_fmac_f32_e32 v26, v218, v138
	s_waitcnt vmcnt(36)
	v_fmac_f32_e32 v26, v219, v139
	s_waitcnt vmcnt(35)
	v_fmac_f32_e32 v26, v220, v140
	s_waitcnt vmcnt(34)
	v_fmac_f32_e32 v26, v221, v141
	s_waitcnt vmcnt(33)
	v_fmac_f32_e32 v26, v222, v142
	s_waitcnt vmcnt(32)
	v_fmac_f32_e32 v26, v223, v143
	ds_read_b128 v[192:195], v226 offset:4096
	ds_read_b128 v[196:199], v226 offset:4112
	ds_read_b128 v[200:203], v226 offset:4128
	ds_read_b128 v[204:207], v226 offset:4144
	ds_read_b128 v[208:211], v226 offset:4160
	ds_read_b128 v[212:215], v226 offset:4176
	ds_read_b128 v[216:219], v226 offset:4192
	ds_read_b128 v[220:223], v226 offset:4208
	s_waitcnt lgkmcnt(0)
	v_fmac_f32_e32 v27, v192, v112
	v_fmac_f32_e32 v27, v193, v113
	v_fmac_f32_e32 v27, v194, v114
	v_fmac_f32_e32 v27, v195, v115
	v_fmac_f32_e32 v27, v196, v116
	v_fmac_f32_e32 v27, v197, v117
	v_fmac_f32_e32 v27, v198, v118
	v_fmac_f32_e32 v27, v199, v119
	v_fmac_f32_e32 v27, v200, v120
	v_fmac_f32_e32 v27, v201, v121
	v_fmac_f32_e32 v27, v202, v122
	v_fmac_f32_e32 v27, v203, v123
	v_fmac_f32_e32 v27, v204, v124
	v_fmac_f32_e32 v27, v205, v125
	v_fmac_f32_e32 v27, v206, v126
	v_fmac_f32_e32 v27, v207, v127
	v_fmac_f32_e32 v27, v208, v128
	v_fmac_f32_e32 v27, v209, v129
	v_fmac_f32_e32 v27, v210, v130
	v_fmac_f32_e32 v27, v211, v131
	v_fmac_f32_e32 v27, v212, v132
	v_fmac_f32_e32 v27, v213, v133
	v_fmac_f32_e32 v27, v214, v134
	v_fmac_f32_e32 v27, v215, v135
	v_fmac_f32_e32 v27, v216, v136
	v_fmac_f32_e32 v27, v217, v137
	v_fmac_f32_e32 v27, v218, v138
	v_fmac_f32_e32 v27, v219, v139
	v_fmac_f32_e32 v27, v220, v140
	v_fmac_f32_e32 v27, v221, v141
	v_fmac_f32_e32 v27, v222, v142
	v_fmac_f32_e32 v27, v223, v143
	ds_read_b128 v[192:195], v226 offset:8192
	ds_read_b128 v[196:199], v226 offset:8208
	ds_read_b128 v[200:203], v226 offset:8224
	ds_read_b128 v[204:207], v226 offset:8240
	ds_read_b128 v[208:211], v226 offset:8256
	ds_read_b128 v[212:215], v226 offset:8272
	ds_read_b128 v[216:219], v226 offset:8288
	ds_read_b128 v[220:223], v226 offset:8304
	s_waitcnt lgkmcnt(0)
	v_fmac_f32_e32 v42, v192, v112
	v_fmac_f32_e32 v42, v193, v113
	v_fmac_f32_e32 v42, v194, v114
	v_fmac_f32_e32 v42, v195, v115
	v_fmac_f32_e32 v42, v196, v116
	v_fmac_f32_e32 v42, v197, v117
	v_fmac_f32_e32 v42, v198, v118
	v_fmac_f32_e32 v42, v199, v119
	v_fmac_f32_e32 v42, v200, v120
	v_fmac_f32_e32 v42, v201, v121
	v_fmac_f32_e32 v42, v202, v122
	v_fmac_f32_e32 v42, v203, v123
	v_fmac_f32_e32 v42, v204, v124
	v_fmac_f32_e32 v42, v205, v125
	v_fmac_f32_e32 v42, v206, v126
	v_fmac_f32_e32 v42, v207, v127
	v_fmac_f32_e32 v42, v208, v128
	v_fmac_f32_e32 v42, v209, v129
	v_fmac_f32_e32 v42, v210, v130
	v_fmac_f32_e32 v42, v211, v131
	v_fmac_f32_e32 v42, v212, v132
	v_fmac_f32_e32 v42, v213, v133
	v_fmac_f32_e32 v42, v214, v134
	v_fmac_f32_e32 v42, v215, v135
	v_fmac_f32_e32 v42, v216, v136
	v_fmac_f32_e32 v42, v217, v137
	v_fmac_f32_e32 v42, v218, v138
	v_fmac_f32_e32 v42, v219, v139
	v_fmac_f32_e32 v42, v220, v140
	v_fmac_f32_e32 v42, v221, v141
	v_fmac_f32_e32 v42, v222, v142
	v_fmac_f32_e32 v42, v223, v143
	ds_read_b128 v[192:195], v226 offset:12288
	ds_read_b128 v[196:199], v226 offset:12304
	ds_read_b128 v[200:203], v226 offset:12320
	ds_read_b128 v[204:207], v226 offset:12336
	ds_read_b128 v[208:211], v226 offset:12352
	ds_read_b128 v[212:215], v226 offset:12368
	ds_read_b128 v[216:219], v226 offset:12384
	ds_read_b128 v[220:223], v226 offset:12400
	s_waitcnt lgkmcnt(0)
	v_fmac_f32_e32 v43, v192, v112
	v_fmac_f32_e32 v43, v193, v113
	v_fmac_f32_e32 v43, v194, v114
	v_fmac_f32_e32 v43, v195, v115
	v_fmac_f32_e32 v43, v196, v116
	v_fmac_f32_e32 v43, v197, v117
	v_fmac_f32_e32 v43, v198, v118
	v_fmac_f32_e32 v43, v199, v119
	v_fmac_f32_e32 v43, v200, v120
	v_fmac_f32_e32 v43, v201, v121
	v_fmac_f32_e32 v43, v202, v122
	v_fmac_f32_e32 v43, v203, v123
	v_fmac_f32_e32 v43, v204, v124
	v_fmac_f32_e32 v43, v205, v125
	v_fmac_f32_e32 v43, v206, v126
	v_fmac_f32_e32 v43, v207, v127
	v_fmac_f32_e32 v43, v208, v128
	v_fmac_f32_e32 v43, v209, v129
	v_fmac_f32_e32 v43, v210, v130
	v_fmac_f32_e32 v43, v211, v131
	v_fmac_f32_e32 v43, v212, v132
	v_fmac_f32_e32 v43, v213, v133
	v_fmac_f32_e32 v43, v214, v134
	v_fmac_f32_e32 v43, v215, v135
	v_fmac_f32_e32 v43, v216, v136
	v_fmac_f32_e32 v43, v217, v137
	v_fmac_f32_e32 v43, v218, v138
	v_fmac_f32_e32 v43, v219, v139
	v_fmac_f32_e32 v43, v220, v140
	v_fmac_f32_e32 v43, v221, v141
	v_fmac_f32_e32 v43, v222, v142
	v_fmac_f32_e32 v43, v223, v143
	ds_read_b128 v[192:195], v226 offset:16384
	ds_read_b128 v[196:199], v226 offset:16400
	ds_read_b128 v[200:203], v226 offset:16416
	ds_read_b128 v[204:207], v226 offset:16432
	ds_read_b128 v[208:211], v226 offset:16448
	ds_read_b128 v[212:215], v226 offset:16464
	ds_read_b128 v[216:219], v226 offset:16480
	ds_read_b128 v[220:223], v226 offset:16496
	s_waitcnt lgkmcnt(0)
	v_fmac_f32_e32 v16, v192, v112
	v_fmac_f32_e32 v16, v193, v113
	v_fmac_f32_e32 v16, v194, v114
	v_fmac_f32_e32 v16, v195, v115
	v_fmac_f32_e32 v16, v196, v116
	v_fmac_f32_e32 v16, v197, v117
	v_fmac_f32_e32 v16, v198, v118
	v_fmac_f32_e32 v16, v199, v119
	v_fmac_f32_e32 v16, v200, v120
	v_fmac_f32_e32 v16, v201, v121
	v_fmac_f32_e32 v16, v202, v122
	v_fmac_f32_e32 v16, v203, v123
	v_fmac_f32_e32 v16, v204, v124
	v_fmac_f32_e32 v16, v205, v125
	v_fmac_f32_e32 v16, v206, v126
	v_fmac_f32_e32 v16, v207, v127
	v_fmac_f32_e32 v16, v208, v128
	v_fmac_f32_e32 v16, v209, v129
	v_fmac_f32_e32 v16, v210, v130
	v_fmac_f32_e32 v16, v211, v131
	v_fmac_f32_e32 v16, v212, v132
	v_fmac_f32_e32 v16, v213, v133
	v_fmac_f32_e32 v16, v214, v134
	v_fmac_f32_e32 v16, v215, v135
	v_fmac_f32_e32 v16, v216, v136
	v_fmac_f32_e32 v16, v217, v137
	v_fmac_f32_e32 v16, v218, v138
	v_fmac_f32_e32 v16, v219, v139
	v_fmac_f32_e32 v16, v220, v140
	v_fmac_f32_e32 v16, v221, v141
	v_fmac_f32_e32 v16, v222, v142
	v_fmac_f32_e32 v16, v223, v143
	ds_read_b128 v[192:195], v226 offset:20480
	ds_read_b128 v[196:199], v226 offset:20496
	ds_read_b128 v[200:203], v226 offset:20512
	ds_read_b128 v[204:207], v226 offset:20528
	ds_read_b128 v[208:211], v226 offset:20544
	ds_read_b128 v[212:215], v226 offset:20560
	ds_read_b128 v[216:219], v226 offset:20576
	ds_read_b128 v[220:223], v226 offset:20592
	s_waitcnt lgkmcnt(0)
	v_fmac_f32_e32 v17, v192, v112
	v_fmac_f32_e32 v17, v193, v113
	v_fmac_f32_e32 v17, v194, v114
	v_fmac_f32_e32 v17, v195, v115
	v_fmac_f32_e32 v17, v196, v116
	v_fmac_f32_e32 v17, v197, v117
	v_fmac_f32_e32 v17, v198, v118
	v_fmac_f32_e32 v17, v199, v119
	v_fmac_f32_e32 v17, v200, v120
	v_fmac_f32_e32 v17, v201, v121
	v_fmac_f32_e32 v17, v202, v122
	v_fmac_f32_e32 v17, v203, v123
	v_fmac_f32_e32 v17, v204, v124
	v_fmac_f32_e32 v17, v205, v125
	v_fmac_f32_e32 v17, v206, v126
	v_fmac_f32_e32 v17, v207, v127
	v_fmac_f32_e32 v17, v208, v128
	v_fmac_f32_e32 v17, v209, v129
	v_fmac_f32_e32 v17, v210, v130
	v_fmac_f32_e32 v17, v211, v131
	v_fmac_f32_e32 v17, v212, v132
	v_fmac_f32_e32 v17, v213, v133
	v_fmac_f32_e32 v17, v214, v134
	v_fmac_f32_e32 v17, v215, v135
	v_fmac_f32_e32 v17, v216, v136
	v_fmac_f32_e32 v17, v217, v137
	v_fmac_f32_e32 v17, v218, v138
	v_fmac_f32_e32 v17, v219, v139
	v_fmac_f32_e32 v17, v220, v140
	v_fmac_f32_e32 v17, v221, v141
	v_fmac_f32_e32 v17, v222, v142
	v_fmac_f32_e32 v17, v223, v143
	ds_read_b128 v[192:195], v226 offset:24576
	ds_read_b128 v[196:199], v226 offset:24592
	ds_read_b128 v[200:203], v226 offset:24608
	ds_read_b128 v[204:207], v226 offset:24624
	ds_read_b128 v[208:211], v226 offset:24640
	ds_read_b128 v[212:215], v226 offset:24656
	ds_read_b128 v[216:219], v226 offset:24672
	ds_read_b128 v[220:223], v226 offset:24688
	s_waitcnt lgkmcnt(0)
	v_fmac_f32_e32 v14, v192, v112
	v_fmac_f32_e32 v14, v193, v113
	v_fmac_f32_e32 v14, v194, v114
	v_fmac_f32_e32 v14, v195, v115
	v_fmac_f32_e32 v14, v196, v116
	v_fmac_f32_e32 v14, v197, v117
	v_fmac_f32_e32 v14, v198, v118
	v_fmac_f32_e32 v14, v199, v119
	v_fmac_f32_e32 v14, v200, v120
	v_fmac_f32_e32 v14, v201, v121
	v_fmac_f32_e32 v14, v202, v122
	v_fmac_f32_e32 v14, v203, v123
	v_fmac_f32_e32 v14, v204, v124
	v_fmac_f32_e32 v14, v205, v125
	v_fmac_f32_e32 v14, v206, v126
	v_fmac_f32_e32 v14, v207, v127
	v_fmac_f32_e32 v14, v208, v128
	v_fmac_f32_e32 v14, v209, v129
	v_fmac_f32_e32 v14, v210, v130
	v_fmac_f32_e32 v14, v211, v131
	v_fmac_f32_e32 v14, v212, v132
	v_fmac_f32_e32 v14, v213, v133
	v_fmac_f32_e32 v14, v214, v134
	v_fmac_f32_e32 v14, v215, v135
	v_fmac_f32_e32 v14, v216, v136
	v_fmac_f32_e32 v14, v217, v137
	v_fmac_f32_e32 v14, v218, v138
	v_fmac_f32_e32 v14, v219, v139
	v_fmac_f32_e32 v14, v220, v140
	v_fmac_f32_e32 v14, v221, v141
	v_fmac_f32_e32 v14, v222, v142
	v_fmac_f32_e32 v14, v223, v143
	ds_read_b128 v[192:195], v226 offset:28672
	ds_read_b128 v[196:199], v226 offset:28688
	ds_read_b128 v[200:203], v226 offset:28704
	ds_read_b128 v[204:207], v226 offset:28720
	ds_read_b128 v[208:211], v226 offset:28736
	ds_read_b128 v[212:215], v226 offset:28752
	ds_read_b128 v[216:219], v226 offset:28768
	ds_read_b128 v[220:223], v226 offset:28784
	s_waitcnt lgkmcnt(0)
	v_fmac_f32_e32 v15, v192, v112
	v_fmac_f32_e32 v15, v193, v113
	v_fmac_f32_e32 v15, v194, v114
	v_fmac_f32_e32 v15, v195, v115
	v_fmac_f32_e32 v15, v196, v116
	v_fmac_f32_e32 v15, v197, v117
	v_fmac_f32_e32 v15, v198, v118
	v_fmac_f32_e32 v15, v199, v119
	v_fmac_f32_e32 v15, v200, v120
	v_fmac_f32_e32 v15, v201, v121
	v_fmac_f32_e32 v15, v202, v122
	v_fmac_f32_e32 v15, v203, v123
	v_fmac_f32_e32 v15, v204, v124
	v_fmac_f32_e32 v15, v205, v125
	v_fmac_f32_e32 v15, v206, v126
	v_fmac_f32_e32 v15, v207, v127
	v_fmac_f32_e32 v15, v208, v128
	v_fmac_f32_e32 v15, v209, v129
	v_fmac_f32_e32 v15, v210, v130
	v_fmac_f32_e32 v15, v211, v131
	v_fmac_f32_e32 v15, v212, v132
	v_fmac_f32_e32 v15, v213, v133
	v_fmac_f32_e32 v15, v214, v134
	v_fmac_f32_e32 v15, v215, v135
	v_fmac_f32_e32 v15, v216, v136
	v_fmac_f32_e32 v15, v217, v137
	v_fmac_f32_e32 v15, v218, v138
	v_fmac_f32_e32 v15, v219, v139
	v_fmac_f32_e32 v15, v220, v140
	v_fmac_f32_e32 v15, v221, v141
	v_fmac_f32_e32 v15, v222, v142
	v_fmac_f32_e32 v15, v223, v143
	s_add_i32 s8, s8, 32
	s_waitcnt vmcnt(31)
	v_lshl_add_u64 v[224:225], s[18:19], 2, v[48:49]
	global_load_dword v112, v[224:225], off
	s_add_u32 s18, s18, s12
	s_addc_u32 s19, s19, 0
	v_lshl_add_u64 v[224:225], s[18:19], 2, v[48:49]
	global_load_dword v113, v[224:225], off
	s_add_u32 s18, s18, s12
	s_addc_u32 s19, s19, 0
	v_lshl_add_u64 v[224:225], s[18:19], 2, v[48:49]
	global_load_dword v114, v[224:225], off
	s_add_u32 s18, s18, s12
	s_addc_u32 s19, s19, 0
	v_lshl_add_u64 v[224:225], s[18:19], 2, v[48:49]
	global_load_dword v115, v[224:225], off
	s_add_u32 s18, s18, s12
	s_addc_u32 s19, s19, 0
	v_lshl_add_u64 v[224:225], s[18:19], 2, v[48:49]
	global_load_dword v116, v[224:225], off
	s_add_u32 s18, s18, s12
	s_addc_u32 s19, s19, 0
	v_lshl_add_u64 v[224:225], s[18:19], 2, v[48:49]
	global_load_dword v117, v[224:225], off
	s_add_u32 s18, s18, s12
	s_addc_u32 s19, s19, 0
	v_lshl_add_u64 v[224:225], s[18:19], 2, v[48:49]
	global_load_dword v118, v[224:225], off
	s_add_u32 s18, s18, s12
	s_addc_u32 s19, s19, 0
	v_lshl_add_u64 v[224:225], s[18:19], 2, v[48:49]
	global_load_dword v119, v[224:225], off
	s_add_u32 s18, s18, s12
	s_addc_u32 s19, s19, 0
	v_lshl_add_u64 v[224:225], s[18:19], 2, v[48:49]
	global_load_dword v120, v[224:225], off
	s_add_u32 s18, s18, s12
	s_addc_u32 s19, s19, 0
	v_lshl_add_u64 v[224:225], s[18:19], 2, v[48:49]
	global_load_dword v121, v[224:225], off
	s_add_u32 s18, s18, s12
	s_addc_u32 s19, s19, 0
	v_lshl_add_u64 v[224:225], s[18:19], 2, v[48:49]
	global_load_dword v122, v[224:225], off
	s_add_u32 s18, s18, s12
	s_addc_u32 s19, s19, 0
	v_lshl_add_u64 v[224:225], s[18:19], 2, v[48:49]
	global_load_dword v123, v[224:225], off
	s_add_u32 s18, s18, s12
	s_addc_u32 s19, s19, 0
	v_lshl_add_u64 v[224:225], s[18:19], 2, v[48:49]
	global_load_dword v124, v[224:225], off
	s_add_u32 s18, s18, s12
	s_addc_u32 s19, s19, 0
	v_lshl_add_u64 v[224:225], s[18:19], 2, v[48:49]
	global_load_dword v125, v[224:225], off
	s_add_u32 s18, s18, s12
	s_addc_u32 s19, s19, 0
	v_lshl_add_u64 v[224:225], s[18:19], 2, v[48:49]
	global_load_dword v126, v[224:225], off
	s_add_u32 s18, s18, s12
	s_addc_u32 s19, s19, 0
	v_lshl_add_u64 v[224:225], s[18:19], 2, v[48:49]
	global_load_dword v127, v[224:225], off
	s_add_u32 s18, s18, s12
	s_addc_u32 s19, s19, 0
	v_lshl_add_u64 v[224:225], s[18:19], 2, v[48:49]
	global_load_dword v128, v[224:225], off
	s_add_u32 s18, s18, s12
	s_addc_u32 s19, s19, 0
	v_lshl_add_u64 v[224:225], s[18:19], 2, v[48:49]
	global_load_dword v129, v[224:225], off
	s_add_u32 s18, s18, s12
	s_addc_u32 s19, s19, 0
	v_lshl_add_u64 v[224:225], s[18:19], 2, v[48:49]
	global_load_dword v130, v[224:225], off
	s_add_u32 s18, s18, s12
	s_addc_u32 s19, s19, 0
	v_lshl_add_u64 v[224:225], s[18:19], 2, v[48:49]
	global_load_dword v131, v[224:225], off
	s_add_u32 s18, s18, s12
	s_addc_u32 s19, s19, 0
	v_lshl_add_u64 v[224:225], s[18:19], 2, v[48:49]
	global_load_dword v132, v[224:225], off
	s_add_u32 s18, s18, s12
	s_addc_u32 s19, s19, 0
	v_lshl_add_u64 v[224:225], s[18:19], 2, v[48:49]
	global_load_dword v133, v[224:225], off
	s_add_u32 s18, s18, s12
	s_addc_u32 s19, s19, 0
	v_lshl_add_u64 v[224:225], s[18:19], 2, v[48:49]
	global_load_dword v134, v[224:225], off
	s_add_u32 s18, s18, s12
	s_addc_u32 s19, s19, 0
	v_lshl_add_u64 v[224:225], s[18:19], 2, v[48:49]
	global_load_dword v135, v[224:225], off
	s_add_u32 s18, s18, s12
	s_addc_u32 s19, s19, 0
	v_lshl_add_u64 v[224:225], s[18:19], 2, v[48:49]
	global_load_dword v136, v[224:225], off
	s_add_u32 s18, s18, s12
	s_addc_u32 s19, s19, 0
	v_lshl_add_u64 v[224:225], s[18:19], 2, v[48:49]
	global_load_dword v137, v[224:225], off
	s_add_u32 s18, s18, s12
	s_addc_u32 s19, s19, 0
	v_lshl_add_u64 v[224:225], s[18:19], 2, v[48:49]
	global_load_dword v138, v[224:225], off
	s_add_u32 s18, s18, s12
	s_addc_u32 s19, s19, 0
	v_lshl_add_u64 v[224:225], s[18:19], 2, v[48:49]
	global_load_dword v139, v[224:225], off
	s_add_u32 s18, s18, s12
	s_addc_u32 s19, s19, 0
	v_lshl_add_u64 v[224:225], s[18:19], 2, v[48:49]
	global_load_dword v140, v[224:225], off
	s_add_u32 s18, s18, s12
	s_addc_u32 s19, s19, 0
	v_lshl_add_u64 v[224:225], s[18:19], 2, v[48:49]
	global_load_dword v141, v[224:225], off
	s_add_u32 s18, s18, s12
	s_addc_u32 s19, s19, 0
	v_lshl_add_u64 v[224:225], s[18:19], 2, v[48:49]
	global_load_dword v142, v[224:225], off
	s_add_u32 s18, s18, s12
	s_addc_u32 s19, s19, 0
	v_lshl_add_u64 v[224:225], s[18:19], 2, v[48:49]
	global_load_dword v143, v[224:225], off
	s_add_u32 s18, s18, s12
	s_addc_u32 s19, s19, 0
	s_lshl_b32 s9, s8, 2
	s_add_i32 s9, s15, s9
	v_mov_b32_e32 v226, s9
	ds_read_b128 v[192:195], v226
	ds_read_b128 v[196:199], v226 offset:16
	ds_read_b128 v[200:203], v226 offset:32
	ds_read_b128 v[204:207], v226 offset:48
	ds_read_b128 v[208:211], v226 offset:64
	ds_read_b128 v[212:215], v226 offset:80
	ds_read_b128 v[216:219], v226 offset:96
	ds_read_b128 v[220:223], v226 offset:112
	s_waitcnt lgkmcnt(0)
	s_waitcnt vmcnt(63)
	v_fmac_f32_e32 v26, v192, v82
	s_waitcnt vmcnt(62)
	v_fmac_f32_e32 v26, v193, v83
	s_waitcnt vmcnt(61)
	v_fmac_f32_e32 v26, v194, v84
	s_waitcnt vmcnt(60)
	v_fmac_f32_e32 v26, v195, v85
	s_waitcnt vmcnt(59)
	v_fmac_f32_e32 v26, v196, v86
	s_waitcnt vmcnt(58)
	v_fmac_f32_e32 v26, v197, v87
	s_waitcnt vmcnt(57)
	v_fmac_f32_e32 v26, v198, v88
	s_waitcnt vmcnt(56)
	v_fmac_f32_e32 v26, v199, v89
	s_waitcnt vmcnt(55)
	v_fmac_f32_e32 v26, v200, v90
	s_waitcnt vmcnt(54)
	v_fmac_f32_e32 v26, v201, v91
	s_waitcnt vmcnt(53)
	v_fmac_f32_e32 v26, v202, v92
	s_waitcnt vmcnt(52)
	v_fmac_f32_e32 v26, v203, v93
	s_waitcnt vmcnt(51)
	v_fmac_f32_e32 v26, v204, v94
	s_waitcnt vmcnt(50)
	v_fmac_f32_e32 v26, v205, v95
	s_waitcnt vmcnt(49)
	v_fmac_f32_e32 v26, v206, v96
	s_waitcnt vmcnt(48)
	v_fmac_f32_e32 v26, v207, v97
	s_waitcnt vmcnt(47)
	v_fmac_f32_e32 v26, v208, v98
	s_waitcnt vmcnt(46)
	v_fmac_f32_e32 v26, v209, v99
	s_waitcnt vmcnt(45)
	v_fmac_f32_e32 v26, v210, v100
	s_waitcnt vmcnt(44)
	v_fmac_f32_e32 v26, v211, v101
	s_waitcnt vmcnt(43)
	v_fmac_f32_e32 v26, v212, v102
	s_waitcnt vmcnt(42)
	v_fmac_f32_e32 v26, v213, v103
	s_waitcnt vmcnt(41)
	v_fmac_f32_e32 v26, v214, v104
	s_waitcnt vmcnt(40)
	v_fmac_f32_e32 v26, v215, v105
	s_waitcnt vmcnt(39)
	v_fmac_f32_e32 v26, v216, v106
	s_waitcnt vmcnt(38)
	v_fmac_f32_e32 v26, v217, v107
	s_waitcnt vmcnt(37)
	v_fmac_f32_e32 v26, v218, v108
	s_waitcnt vmcnt(36)
	v_fmac_f32_e32 v26, v219, v109
	s_waitcnt vmcnt(35)
	v_fmac_f32_e32 v26, v220, v110
	s_waitcnt vmcnt(34)
	v_fmac_f32_e32 v26, v221, v111
	s_waitcnt vmcnt(33)
	v_fmac_f32_e32 v26, v222, v144
	s_waitcnt vmcnt(32)
	v_fmac_f32_e32 v26, v223, v145
	ds_read_b128 v[192:195], v226 offset:4096
	ds_read_b128 v[196:199], v226 offset:4112
	ds_read_b128 v[200:203], v226 offset:4128
	ds_read_b128 v[204:207], v226 offset:4144
	ds_read_b128 v[208:211], v226 offset:4160
	ds_read_b128 v[212:215], v226 offset:4176
	ds_read_b128 v[216:219], v226 offset:4192
	ds_read_b128 v[220:223], v226 offset:4208
	s_waitcnt lgkmcnt(0)
	v_fmac_f32_e32 v27, v192, v82
	v_fmac_f32_e32 v27, v193, v83
	v_fmac_f32_e32 v27, v194, v84
	v_fmac_f32_e32 v27, v195, v85
	v_fmac_f32_e32 v27, v196, v86
	v_fmac_f32_e32 v27, v197, v87
	v_fmac_f32_e32 v27, v198, v88
	v_fmac_f32_e32 v27, v199, v89
	v_fmac_f32_e32 v27, v200, v90
	v_fmac_f32_e32 v27, v201, v91
	v_fmac_f32_e32 v27, v202, v92
	v_fmac_f32_e32 v27, v203, v93
	v_fmac_f32_e32 v27, v204, v94
	v_fmac_f32_e32 v27, v205, v95
	v_fmac_f32_e32 v27, v206, v96
	v_fmac_f32_e32 v27, v207, v97
	v_fmac_f32_e32 v27, v208, v98
	v_fmac_f32_e32 v27, v209, v99
	v_fmac_f32_e32 v27, v210, v100
	v_fmac_f32_e32 v27, v211, v101
	v_fmac_f32_e32 v27, v212, v102
	v_fmac_f32_e32 v27, v213, v103
	v_fmac_f32_e32 v27, v214, v104
	v_fmac_f32_e32 v27, v215, v105
	v_fmac_f32_e32 v27, v216, v106
	v_fmac_f32_e32 v27, v217, v107
	v_fmac_f32_e32 v27, v218, v108
	v_fmac_f32_e32 v27, v219, v109
	v_fmac_f32_e32 v27, v220, v110
	v_fmac_f32_e32 v27, v221, v111
	v_fmac_f32_e32 v27, v222, v144
	v_fmac_f32_e32 v27, v223, v145
	ds_read_b128 v[192:195], v226 offset:8192
	ds_read_b128 v[196:199], v226 offset:8208
	ds_read_b128 v[200:203], v226 offset:8224
	ds_read_b128 v[204:207], v226 offset:8240
	ds_read_b128 v[208:211], v226 offset:8256
	ds_read_b128 v[212:215], v226 offset:8272
	ds_read_b128 v[216:219], v226 offset:8288
	ds_read_b128 v[220:223], v226 offset:8304
	s_waitcnt lgkmcnt(0)
	v_fmac_f32_e32 v42, v192, v82
	v_fmac_f32_e32 v42, v193, v83
	v_fmac_f32_e32 v42, v194, v84
	v_fmac_f32_e32 v42, v195, v85
	v_fmac_f32_e32 v42, v196, v86
	v_fmac_f32_e32 v42, v197, v87
	v_fmac_f32_e32 v42, v198, v88
	v_fmac_f32_e32 v42, v199, v89
	v_fmac_f32_e32 v42, v200, v90
	v_fmac_f32_e32 v42, v201, v91
	v_fmac_f32_e32 v42, v202, v92
	v_fmac_f32_e32 v42, v203, v93
	v_fmac_f32_e32 v42, v204, v94
	v_fmac_f32_e32 v42, v205, v95
	v_fmac_f32_e32 v42, v206, v96
	v_fmac_f32_e32 v42, v207, v97
	v_fmac_f32_e32 v42, v208, v98
	v_fmac_f32_e32 v42, v209, v99
	v_fmac_f32_e32 v42, v210, v100
	v_fmac_f32_e32 v42, v211, v101
	v_fmac_f32_e32 v42, v212, v102
	v_fmac_f32_e32 v42, v213, v103
	v_fmac_f32_e32 v42, v214, v104
	v_fmac_f32_e32 v42, v215, v105
	v_fmac_f32_e32 v42, v216, v106
	v_fmac_f32_e32 v42, v217, v107
	v_fmac_f32_e32 v42, v218, v108
	v_fmac_f32_e32 v42, v219, v109
	v_fmac_f32_e32 v42, v220, v110
	v_fmac_f32_e32 v42, v221, v111
	v_fmac_f32_e32 v42, v222, v144
	v_fmac_f32_e32 v42, v223, v145
	ds_read_b128 v[192:195], v226 offset:12288
	ds_read_b128 v[196:199], v226 offset:12304
	ds_read_b128 v[200:203], v226 offset:12320
	ds_read_b128 v[204:207], v226 offset:12336
	ds_read_b128 v[208:211], v226 offset:12352
	ds_read_b128 v[212:215], v226 offset:12368
	ds_read_b128 v[216:219], v226 offset:12384
	ds_read_b128 v[220:223], v226 offset:12400
	s_waitcnt lgkmcnt(0)
	v_fmac_f32_e32 v43, v192, v82
	v_fmac_f32_e32 v43, v193, v83
	v_fmac_f32_e32 v43, v194, v84
	v_fmac_f32_e32 v43, v195, v85
	v_fmac_f32_e32 v43, v196, v86
	v_fmac_f32_e32 v43, v197, v87
	v_fmac_f32_e32 v43, v198, v88
	v_fmac_f32_e32 v43, v199, v89
	v_fmac_f32_e32 v43, v200, v90
	v_fmac_f32_e32 v43, v201, v91
	v_fmac_f32_e32 v43, v202, v92
	v_fmac_f32_e32 v43, v203, v93
	v_fmac_f32_e32 v43, v204, v94
	v_fmac_f32_e32 v43, v205, v95
	v_fmac_f32_e32 v43, v206, v96
	v_fmac_f32_e32 v43, v207, v97
	v_fmac_f32_e32 v43, v208, v98
	v_fmac_f32_e32 v43, v209, v99
	v_fmac_f32_e32 v43, v210, v100
	v_fmac_f32_e32 v43, v211, v101
	v_fmac_f32_e32 v43, v212, v102
	v_fmac_f32_e32 v43, v213, v103
	v_fmac_f32_e32 v43, v214, v104
	v_fmac_f32_e32 v43, v215, v105
	v_fmac_f32_e32 v43, v216, v106
	v_fmac_f32_e32 v43, v217, v107
	v_fmac_f32_e32 v43, v218, v108
	v_fmac_f32_e32 v43, v219, v109
	v_fmac_f32_e32 v43, v220, v110
	v_fmac_f32_e32 v43, v221, v111
	v_fmac_f32_e32 v43, v222, v144
	v_fmac_f32_e32 v43, v223, v145
	ds_read_b128 v[192:195], v226 offset:16384
	ds_read_b128 v[196:199], v226 offset:16400
	ds_read_b128 v[200:203], v226 offset:16416
	ds_read_b128 v[204:207], v226 offset:16432
	ds_read_b128 v[208:211], v226 offset:16448
	ds_read_b128 v[212:215], v226 offset:16464
	ds_read_b128 v[216:219], v226 offset:16480
	ds_read_b128 v[220:223], v226 offset:16496
	s_waitcnt lgkmcnt(0)
	v_fmac_f32_e32 v16, v192, v82
	v_fmac_f32_e32 v16, v193, v83
	v_fmac_f32_e32 v16, v194, v84
	v_fmac_f32_e32 v16, v195, v85
	v_fmac_f32_e32 v16, v196, v86
	v_fmac_f32_e32 v16, v197, v87
	v_fmac_f32_e32 v16, v198, v88
	v_fmac_f32_e32 v16, v199, v89
	v_fmac_f32_e32 v16, v200, v90
	v_fmac_f32_e32 v16, v201, v91
	v_fmac_f32_e32 v16, v202, v92
	v_fmac_f32_e32 v16, v203, v93
	v_fmac_f32_e32 v16, v204, v94
	v_fmac_f32_e32 v16, v205, v95
	v_fmac_f32_e32 v16, v206, v96
	v_fmac_f32_e32 v16, v207, v97
	v_fmac_f32_e32 v16, v208, v98
	v_fmac_f32_e32 v16, v209, v99
	v_fmac_f32_e32 v16, v210, v100
	v_fmac_f32_e32 v16, v211, v101
	v_fmac_f32_e32 v16, v212, v102
	v_fmac_f32_e32 v16, v213, v103
	v_fmac_f32_e32 v16, v214, v104
	v_fmac_f32_e32 v16, v215, v105
	v_fmac_f32_e32 v16, v216, v106
	v_fmac_f32_e32 v16, v217, v107
	v_fmac_f32_e32 v16, v218, v108
	v_fmac_f32_e32 v16, v219, v109
	v_fmac_f32_e32 v16, v220, v110
	v_fmac_f32_e32 v16, v221, v111
	v_fmac_f32_e32 v16, v222, v144
	v_fmac_f32_e32 v16, v223, v145
	ds_read_b128 v[192:195], v226 offset:20480
	ds_read_b128 v[196:199], v226 offset:20496
	ds_read_b128 v[200:203], v226 offset:20512
	ds_read_b128 v[204:207], v226 offset:20528
	ds_read_b128 v[208:211], v226 offset:20544
	ds_read_b128 v[212:215], v226 offset:20560
	ds_read_b128 v[216:219], v226 offset:20576
	ds_read_b128 v[220:223], v226 offset:20592
	s_waitcnt lgkmcnt(0)
	v_fmac_f32_e32 v17, v192, v82
	v_fmac_f32_e32 v17, v193, v83
	v_fmac_f32_e32 v17, v194, v84
	v_fmac_f32_e32 v17, v195, v85
	v_fmac_f32_e32 v17, v196, v86
	v_fmac_f32_e32 v17, v197, v87
	v_fmac_f32_e32 v17, v198, v88
	v_fmac_f32_e32 v17, v199, v89
	v_fmac_f32_e32 v17, v200, v90
	v_fmac_f32_e32 v17, v201, v91
	v_fmac_f32_e32 v17, v202, v92
	v_fmac_f32_e32 v17, v203, v93
	v_fmac_f32_e32 v17, v204, v94
	v_fmac_f32_e32 v17, v205, v95
	v_fmac_f32_e32 v17, v206, v96
	v_fmac_f32_e32 v17, v207, v97
	v_fmac_f32_e32 v17, v208, v98
	v_fmac_f32_e32 v17, v209, v99
	v_fmac_f32_e32 v17, v210, v100
	v_fmac_f32_e32 v17, v211, v101
	v_fmac_f32_e32 v17, v212, v102
	v_fmac_f32_e32 v17, v213, v103
	v_fmac_f32_e32 v17, v214, v104
	v_fmac_f32_e32 v17, v215, v105
	v_fmac_f32_e32 v17, v216, v106
	v_fmac_f32_e32 v17, v217, v107
	v_fmac_f32_e32 v17, v218, v108
	v_fmac_f32_e32 v17, v219, v109
	v_fmac_f32_e32 v17, v220, v110
	v_fmac_f32_e32 v17, v221, v111
	v_fmac_f32_e32 v17, v222, v144
	v_fmac_f32_e32 v17, v223, v145
	ds_read_b128 v[192:195], v226 offset:24576
	ds_read_b128 v[196:199], v226 offset:24592
	ds_read_b128 v[200:203], v226 offset:24608
	ds_read_b128 v[204:207], v226 offset:24624
	ds_read_b128 v[208:211], v226 offset:24640
	ds_read_b128 v[212:215], v226 offset:24656
	ds_read_b128 v[216:219], v226 offset:24672
	ds_read_b128 v[220:223], v226 offset:24688
	s_waitcnt lgkmcnt(0)
	v_fmac_f32_e32 v14, v192, v82
	v_fmac_f32_e32 v14, v193, v83
	v_fmac_f32_e32 v14, v194, v84
	v_fmac_f32_e32 v14, v195, v85
	v_fmac_f32_e32 v14, v196, v86
	v_fmac_f32_e32 v14, v197, v87
	v_fmac_f32_e32 v14, v198, v88
	v_fmac_f32_e32 v14, v199, v89
	v_fmac_f32_e32 v14, v200, v90
	v_fmac_f32_e32 v14, v201, v91
	v_fmac_f32_e32 v14, v202, v92
	v_fmac_f32_e32 v14, v203, v93
	v_fmac_f32_e32 v14, v204, v94
	v_fmac_f32_e32 v14, v205, v95
	v_fmac_f32_e32 v14, v206, v96
	v_fmac_f32_e32 v14, v207, v97
	v_fmac_f32_e32 v14, v208, v98
	v_fmac_f32_e32 v14, v209, v99
	v_fmac_f32_e32 v14, v210, v100
	v_fmac_f32_e32 v14, v211, v101
	v_fmac_f32_e32 v14, v212, v102
	v_fmac_f32_e32 v14, v213, v103
	v_fmac_f32_e32 v14, v214, v104
	v_fmac_f32_e32 v14, v215, v105
	v_fmac_f32_e32 v14, v216, v106
	v_fmac_f32_e32 v14, v217, v107
	v_fmac_f32_e32 v14, v218, v108
	v_fmac_f32_e32 v14, v219, v109
	v_fmac_f32_e32 v14, v220, v110
	v_fmac_f32_e32 v14, v221, v111
	v_fmac_f32_e32 v14, v222, v144
	v_fmac_f32_e32 v14, v223, v145
	ds_read_b128 v[192:195], v226 offset:28672
	ds_read_b128 v[196:199], v226 offset:28688
	ds_read_b128 v[200:203], v226 offset:28704
	ds_read_b128 v[204:207], v226 offset:28720
	ds_read_b128 v[208:211], v226 offset:28736
	ds_read_b128 v[212:215], v226 offset:28752
	ds_read_b128 v[216:219], v226 offset:28768
	ds_read_b128 v[220:223], v226 offset:28784
	s_waitcnt lgkmcnt(0)
	v_fmac_f32_e32 v15, v192, v82
	v_fmac_f32_e32 v15, v193, v83
	v_fmac_f32_e32 v15, v194, v84
	v_fmac_f32_e32 v15, v195, v85
	v_fmac_f32_e32 v15, v196, v86
	v_fmac_f32_e32 v15, v197, v87
	v_fmac_f32_e32 v15, v198, v88
	v_fmac_f32_e32 v15, v199, v89
	v_fmac_f32_e32 v15, v200, v90
	v_fmac_f32_e32 v15, v201, v91
	v_fmac_f32_e32 v15, v202, v92
	v_fmac_f32_e32 v15, v203, v93
	v_fmac_f32_e32 v15, v204, v94
	v_fmac_f32_e32 v15, v205, v95
	v_fmac_f32_e32 v15, v206, v96
	v_fmac_f32_e32 v15, v207, v97
	v_fmac_f32_e32 v15, v208, v98
	v_fmac_f32_e32 v15, v209, v99
	v_fmac_f32_e32 v15, v210, v100
	v_fmac_f32_e32 v15, v211, v101
	v_fmac_f32_e32 v15, v212, v102
	v_fmac_f32_e32 v15, v213, v103
	v_fmac_f32_e32 v15, v214, v104
	v_fmac_f32_e32 v15, v215, v105
	v_fmac_f32_e32 v15, v216, v106
	v_fmac_f32_e32 v15, v217, v107
	v_fmac_f32_e32 v15, v218, v108
	v_fmac_f32_e32 v15, v219, v109
	v_fmac_f32_e32 v15, v220, v110
	v_fmac_f32_e32 v15, v221, v111
	v_fmac_f32_e32 v15, v222, v144
	v_fmac_f32_e32 v15, v223, v145
	s_add_i32 s8, s8, 32
	s_waitcnt vmcnt(31)
	v_lshl_add_u64 v[224:225], s[18:19], 2, v[48:49]
	global_load_dword v82, v[224:225], off
	s_add_u32 s18, s18, s12
	s_addc_u32 s19, s19, 0
	v_lshl_add_u64 v[224:225], s[18:19], 2, v[48:49]
	global_load_dword v83, v[224:225], off
	s_add_u32 s18, s18, s12
	s_addc_u32 s19, s19, 0
	v_lshl_add_u64 v[224:225], s[18:19], 2, v[48:49]
	global_load_dword v84, v[224:225], off
	s_add_u32 s18, s18, s12
	s_addc_u32 s19, s19, 0
	v_lshl_add_u64 v[224:225], s[18:19], 2, v[48:49]
	global_load_dword v85, v[224:225], off
	s_add_u32 s18, s18, s12
	s_addc_u32 s19, s19, 0
	v_lshl_add_u64 v[224:225], s[18:19], 2, v[48:49]
	global_load_dword v86, v[224:225], off
	s_add_u32 s18, s18, s12
	s_addc_u32 s19, s19, 0
	v_lshl_add_u64 v[224:225], s[18:19], 2, v[48:49]
	global_load_dword v87, v[224:225], off
	s_add_u32 s18, s18, s12
	s_addc_u32 s19, s19, 0
	v_lshl_add_u64 v[224:225], s[18:19], 2, v[48:49]
	global_load_dword v88, v[224:225], off
	s_add_u32 s18, s18, s12
	s_addc_u32 s19, s19, 0
	v_lshl_add_u64 v[224:225], s[18:19], 2, v[48:49]
	global_load_dword v89, v[224:225], off
	s_add_u32 s18, s18, s12
	s_addc_u32 s19, s19, 0
	v_lshl_add_u64 v[224:225], s[18:19], 2, v[48:49]
	global_load_dword v90, v[224:225], off
	s_add_u32 s18, s18, s12
	s_addc_u32 s19, s19, 0
	v_lshl_add_u64 v[224:225], s[18:19], 2, v[48:49]
	global_load_dword v91, v[224:225], off
	s_add_u32 s18, s18, s12
	s_addc_u32 s19, s19, 0
	v_lshl_add_u64 v[224:225], s[18:19], 2, v[48:49]
	global_load_dword v92, v[224:225], off
	s_add_u32 s18, s18, s12
	s_addc_u32 s19, s19, 0
	v_lshl_add_u64 v[224:225], s[18:19], 2, v[48:49]
	global_load_dword v93, v[224:225], off
	s_add_u32 s18, s18, s12
	s_addc_u32 s19, s19, 0
	v_lshl_add_u64 v[224:225], s[18:19], 2, v[48:49]
	global_load_dword v94, v[224:225], off
	s_add_u32 s18, s18, s12
	s_addc_u32 s19, s19, 0
	v_lshl_add_u64 v[224:225], s[18:19], 2, v[48:49]
	global_load_dword v95, v[224:225], off
	s_add_u32 s18, s18, s12
	s_addc_u32 s19, s19, 0
	v_lshl_add_u64 v[224:225], s[18:19], 2, v[48:49]
	global_load_dword v96, v[224:225], off
	s_add_u32 s18, s18, s12
	s_addc_u32 s19, s19, 0
	v_lshl_add_u64 v[224:225], s[18:19], 2, v[48:49]
	global_load_dword v97, v[224:225], off
	s_add_u32 s18, s18, s12
	s_addc_u32 s19, s19, 0
	v_lshl_add_u64 v[224:225], s[18:19], 2, v[48:49]
	global_load_dword v98, v[224:225], off
	s_add_u32 s18, s18, s12
	s_addc_u32 s19, s19, 0
	v_lshl_add_u64 v[224:225], s[18:19], 2, v[48:49]
	global_load_dword v99, v[224:225], off
	s_add_u32 s18, s18, s12
	s_addc_u32 s19, s19, 0
	v_lshl_add_u64 v[224:225], s[18:19], 2, v[48:49]
	global_load_dword v100, v[224:225], off
	s_add_u32 s18, s18, s12
	s_addc_u32 s19, s19, 0
	v_lshl_add_u64 v[224:225], s[18:19], 2, v[48:49]
	global_load_dword v101, v[224:225], off
	s_add_u32 s18, s18, s12
	s_addc_u32 s19, s19, 0
	v_lshl_add_u64 v[224:225], s[18:19], 2, v[48:49]
	global_load_dword v102, v[224:225], off
	s_add_u32 s18, s18, s12
	s_addc_u32 s19, s19, 0
	v_lshl_add_u64 v[224:225], s[18:19], 2, v[48:49]
	global_load_dword v103, v[224:225], off
	s_add_u32 s18, s18, s12
	s_addc_u32 s19, s19, 0
	v_lshl_add_u64 v[224:225], s[18:19], 2, v[48:49]
	global_load_dword v104, v[224:225], off
	s_add_u32 s18, s18, s12
	s_addc_u32 s19, s19, 0
	v_lshl_add_u64 v[224:225], s[18:19], 2, v[48:49]
	global_load_dword v105, v[224:225], off
	s_add_u32 s18, s18, s12
	s_addc_u32 s19, s19, 0
	v_lshl_add_u64 v[224:225], s[18:19], 2, v[48:49]
	global_load_dword v106, v[224:225], off
	s_add_u32 s18, s18, s12
	s_addc_u32 s19, s19, 0
	v_lshl_add_u64 v[224:225], s[18:19], 2, v[48:49]
	global_load_dword v107, v[224:225], off
	s_add_u32 s18, s18, s12
	s_addc_u32 s19, s19, 0
	v_lshl_add_u64 v[224:225], s[18:19], 2, v[48:49]
	global_load_dword v108, v[224:225], off
	s_add_u32 s18, s18, s12
	s_addc_u32 s19, s19, 0
	v_lshl_add_u64 v[224:225], s[18:19], 2, v[48:49]
	global_load_dword v109, v[224:225], off
	s_add_u32 s18, s18, s12
	s_addc_u32 s19, s19, 0
	v_lshl_add_u64 v[224:225], s[18:19], 2, v[48:49]
	global_load_dword v110, v[224:225], off
	s_add_u32 s18, s18, s12
	s_addc_u32 s19, s19, 0
	v_lshl_add_u64 v[224:225], s[18:19], 2, v[48:49]
	global_load_dword v111, v[224:225], off
	s_add_u32 s18, s18, s12
	s_addc_u32 s19, s19, 0
	v_lshl_add_u64 v[224:225], s[18:19], 2, v[48:49]
	global_load_dword v144, v[224:225], off
	s_add_u32 s18, s18, s12
	s_addc_u32 s19, s19, 0
	v_lshl_add_u64 v[224:225], s[18:19], 2, v[48:49]
	global_load_dword v145, v[224:225], off
	s_add_u32 s18, s18, s12
	s_addc_u32 s19, s19, 0
	s_lshl_b32 s9, s8, 2
	s_add_i32 s9, s15, s9
	v_mov_b32_e32 v226, s9
	ds_read_b128 v[192:195], v226
	ds_read_b128 v[196:199], v226 offset:16
	ds_read_b128 v[200:203], v226 offset:32
	ds_read_b128 v[204:207], v226 offset:48
	ds_read_b128 v[208:211], v226 offset:64
	ds_read_b128 v[212:215], v226 offset:80
	ds_read_b128 v[216:219], v226 offset:96
	ds_read_b128 v[220:223], v226 offset:112
	s_waitcnt lgkmcnt(0)
	s_waitcnt vmcnt(63)
	v_fmac_f32_e32 v26, v192, v112
	s_waitcnt vmcnt(62)
	v_fmac_f32_e32 v26, v193, v113
	s_waitcnt vmcnt(61)
	v_fmac_f32_e32 v26, v194, v114
	s_waitcnt vmcnt(60)
	v_fmac_f32_e32 v26, v195, v115
	s_waitcnt vmcnt(59)
	v_fmac_f32_e32 v26, v196, v116
	s_waitcnt vmcnt(58)
	v_fmac_f32_e32 v26, v197, v117
	s_waitcnt vmcnt(57)
	v_fmac_f32_e32 v26, v198, v118
	s_waitcnt vmcnt(56)
	v_fmac_f32_e32 v26, v199, v119
	s_waitcnt vmcnt(55)
	v_fmac_f32_e32 v26, v200, v120
	s_waitcnt vmcnt(54)
	v_fmac_f32_e32 v26, v201, v121
	s_waitcnt vmcnt(53)
	v_fmac_f32_e32 v26, v202, v122
	s_waitcnt vmcnt(52)
	v_fmac_f32_e32 v26, v203, v123
	s_waitcnt vmcnt(51)
	v_fmac_f32_e32 v26, v204, v124
	s_waitcnt vmcnt(50)
	v_fmac_f32_e32 v26, v205, v125
	s_waitcnt vmcnt(49)
	v_fmac_f32_e32 v26, v206, v126
	s_waitcnt vmcnt(48)
	v_fmac_f32_e32 v26, v207, v127
	s_waitcnt vmcnt(47)
	v_fmac_f32_e32 v26, v208, v128
	s_waitcnt vmcnt(46)
	v_fmac_f32_e32 v26, v209, v129
	s_waitcnt vmcnt(45)
	v_fmac_f32_e32 v26, v210, v130
	s_waitcnt vmcnt(44)
	v_fmac_f32_e32 v26, v211, v131
	s_waitcnt vmcnt(43)
	v_fmac_f32_e32 v26, v212, v132
	s_waitcnt vmcnt(42)
	v_fmac_f32_e32 v26, v213, v133
	s_waitcnt vmcnt(41)
	v_fmac_f32_e32 v26, v214, v134
	s_waitcnt vmcnt(40)
	v_fmac_f32_e32 v26, v215, v135
	s_waitcnt vmcnt(39)
	v_fmac_f32_e32 v26, v216, v136
	s_waitcnt vmcnt(38)
	v_fmac_f32_e32 v26, v217, v137
	s_waitcnt vmcnt(37)
	v_fmac_f32_e32 v26, v218, v138
	s_waitcnt vmcnt(36)
	v_fmac_f32_e32 v26, v219, v139
	s_waitcnt vmcnt(35)
	v_fmac_f32_e32 v26, v220, v140
	s_waitcnt vmcnt(34)
	v_fmac_f32_e32 v26, v221, v141
	s_waitcnt vmcnt(33)
	v_fmac_f32_e32 v26, v222, v142
	s_waitcnt vmcnt(32)
	v_fmac_f32_e32 v26, v223, v143
	ds_read_b128 v[192:195], v226 offset:4096
	ds_read_b128 v[196:199], v226 offset:4112
	ds_read_b128 v[200:203], v226 offset:4128
	ds_read_b128 v[204:207], v226 offset:4144
	ds_read_b128 v[208:211], v226 offset:4160
	ds_read_b128 v[212:215], v226 offset:4176
	ds_read_b128 v[216:219], v226 offset:4192
	ds_read_b128 v[220:223], v226 offset:4208
	s_waitcnt lgkmcnt(0)
	v_fmac_f32_e32 v27, v192, v112
	v_fmac_f32_e32 v27, v193, v113
	v_fmac_f32_e32 v27, v194, v114
	v_fmac_f32_e32 v27, v195, v115
	v_fmac_f32_e32 v27, v196, v116
	v_fmac_f32_e32 v27, v197, v117
	v_fmac_f32_e32 v27, v198, v118
	v_fmac_f32_e32 v27, v199, v119
	v_fmac_f32_e32 v27, v200, v120
	v_fmac_f32_e32 v27, v201, v121
	v_fmac_f32_e32 v27, v202, v122
	v_fmac_f32_e32 v27, v203, v123
	v_fmac_f32_e32 v27, v204, v124
	v_fmac_f32_e32 v27, v205, v125
	v_fmac_f32_e32 v27, v206, v126
	v_fmac_f32_e32 v27, v207, v127
	v_fmac_f32_e32 v27, v208, v128
	v_fmac_f32_e32 v27, v209, v129
	v_fmac_f32_e32 v27, v210, v130
	v_fmac_f32_e32 v27, v211, v131
	v_fmac_f32_e32 v27, v212, v132
	v_fmac_f32_e32 v27, v213, v133
	v_fmac_f32_e32 v27, v214, v134
	v_fmac_f32_e32 v27, v215, v135
	v_fmac_f32_e32 v27, v216, v136
	v_fmac_f32_e32 v27, v217, v137
	v_fmac_f32_e32 v27, v218, v138
	v_fmac_f32_e32 v27, v219, v139
	v_fmac_f32_e32 v27, v220, v140
	v_fmac_f32_e32 v27, v221, v141
	v_fmac_f32_e32 v27, v222, v142
	v_fmac_f32_e32 v27, v223, v143
	ds_read_b128 v[192:195], v226 offset:8192
	ds_read_b128 v[196:199], v226 offset:8208
	ds_read_b128 v[200:203], v226 offset:8224
	ds_read_b128 v[204:207], v226 offset:8240
	ds_read_b128 v[208:211], v226 offset:8256
	ds_read_b128 v[212:215], v226 offset:8272
	ds_read_b128 v[216:219], v226 offset:8288
	ds_read_b128 v[220:223], v226 offset:8304
	s_waitcnt lgkmcnt(0)
	v_fmac_f32_e32 v42, v192, v112
	v_fmac_f32_e32 v42, v193, v113
	v_fmac_f32_e32 v42, v194, v114
	v_fmac_f32_e32 v42, v195, v115
	v_fmac_f32_e32 v42, v196, v116
	v_fmac_f32_e32 v42, v197, v117
	v_fmac_f32_e32 v42, v198, v118
	v_fmac_f32_e32 v42, v199, v119
	v_fmac_f32_e32 v42, v200, v120
	v_fmac_f32_e32 v42, v201, v121
	v_fmac_f32_e32 v42, v202, v122
	v_fmac_f32_e32 v42, v203, v123
	v_fmac_f32_e32 v42, v204, v124
	v_fmac_f32_e32 v42, v205, v125
	v_fmac_f32_e32 v42, v206, v126
	v_fmac_f32_e32 v42, v207, v127
	v_fmac_f32_e32 v42, v208, v128
	v_fmac_f32_e32 v42, v209, v129
	v_fmac_f32_e32 v42, v210, v130
	v_fmac_f32_e32 v42, v211, v131
	v_fmac_f32_e32 v42, v212, v132
	v_fmac_f32_e32 v42, v213, v133
	v_fmac_f32_e32 v42, v214, v134
	v_fmac_f32_e32 v42, v215, v135
	v_fmac_f32_e32 v42, v216, v136
	v_fmac_f32_e32 v42, v217, v137
	v_fmac_f32_e32 v42, v218, v138
	v_fmac_f32_e32 v42, v219, v139
	v_fmac_f32_e32 v42, v220, v140
	v_fmac_f32_e32 v42, v221, v141
	v_fmac_f32_e32 v42, v222, v142
	v_fmac_f32_e32 v42, v223, v143
	ds_read_b128 v[192:195], v226 offset:12288
	ds_read_b128 v[196:199], v226 offset:12304
	ds_read_b128 v[200:203], v226 offset:12320
	ds_read_b128 v[204:207], v226 offset:12336
	ds_read_b128 v[208:211], v226 offset:12352
	ds_read_b128 v[212:215], v226 offset:12368
	ds_read_b128 v[216:219], v226 offset:12384
	ds_read_b128 v[220:223], v226 offset:12400
	s_waitcnt lgkmcnt(0)
	v_fmac_f32_e32 v43, v192, v112
	v_fmac_f32_e32 v43, v193, v113
	v_fmac_f32_e32 v43, v194, v114
	v_fmac_f32_e32 v43, v195, v115
	v_fmac_f32_e32 v43, v196, v116
	v_fmac_f32_e32 v43, v197, v117
	v_fmac_f32_e32 v43, v198, v118
	v_fmac_f32_e32 v43, v199, v119
	v_fmac_f32_e32 v43, v200, v120
	v_fmac_f32_e32 v43, v201, v121
	v_fmac_f32_e32 v43, v202, v122
	v_fmac_f32_e32 v43, v203, v123
	v_fmac_f32_e32 v43, v204, v124
	v_fmac_f32_e32 v43, v205, v125
	v_fmac_f32_e32 v43, v206, v126
	v_fmac_f32_e32 v43, v207, v127
	v_fmac_f32_e32 v43, v208, v128
	v_fmac_f32_e32 v43, v209, v129
	v_fmac_f32_e32 v43, v210, v130
	v_fmac_f32_e32 v43, v211, v131
	v_fmac_f32_e32 v43, v212, v132
	v_fmac_f32_e32 v43, v213, v133
	v_fmac_f32_e32 v43, v214, v134
	v_fmac_f32_e32 v43, v215, v135
	v_fmac_f32_e32 v43, v216, v136
	v_fmac_f32_e32 v43, v217, v137
	v_fmac_f32_e32 v43, v218, v138
	v_fmac_f32_e32 v43, v219, v139
	v_fmac_f32_e32 v43, v220, v140
	v_fmac_f32_e32 v43, v221, v141
	v_fmac_f32_e32 v43, v222, v142
	v_fmac_f32_e32 v43, v223, v143
	ds_read_b128 v[192:195], v226 offset:16384
	ds_read_b128 v[196:199], v226 offset:16400
	ds_read_b128 v[200:203], v226 offset:16416
	ds_read_b128 v[204:207], v226 offset:16432
	ds_read_b128 v[208:211], v226 offset:16448
	ds_read_b128 v[212:215], v226 offset:16464
	ds_read_b128 v[216:219], v226 offset:16480
	ds_read_b128 v[220:223], v226 offset:16496
	s_waitcnt lgkmcnt(0)
	v_fmac_f32_e32 v16, v192, v112
	v_fmac_f32_e32 v16, v193, v113
	v_fmac_f32_e32 v16, v194, v114
	v_fmac_f32_e32 v16, v195, v115
	v_fmac_f32_e32 v16, v196, v116
	v_fmac_f32_e32 v16, v197, v117
	v_fmac_f32_e32 v16, v198, v118
	v_fmac_f32_e32 v16, v199, v119
	v_fmac_f32_e32 v16, v200, v120
	v_fmac_f32_e32 v16, v201, v121
	v_fmac_f32_e32 v16, v202, v122
	v_fmac_f32_e32 v16, v203, v123
	v_fmac_f32_e32 v16, v204, v124
	v_fmac_f32_e32 v16, v205, v125
	v_fmac_f32_e32 v16, v206, v126
	v_fmac_f32_e32 v16, v207, v127
	v_fmac_f32_e32 v16, v208, v128
	v_fmac_f32_e32 v16, v209, v129
	v_fmac_f32_e32 v16, v210, v130
	v_fmac_f32_e32 v16, v211, v131
	v_fmac_f32_e32 v16, v212, v132
	v_fmac_f32_e32 v16, v213, v133
	v_fmac_f32_e32 v16, v214, v134
	v_fmac_f32_e32 v16, v215, v135
	v_fmac_f32_e32 v16, v216, v136
	v_fmac_f32_e32 v16, v217, v137
	v_fmac_f32_e32 v16, v218, v138
	v_fmac_f32_e32 v16, v219, v139
	v_fmac_f32_e32 v16, v220, v140
	v_fmac_f32_e32 v16, v221, v141
	v_fmac_f32_e32 v16, v222, v142
	v_fmac_f32_e32 v16, v223, v143
	ds_read_b128 v[192:195], v226 offset:20480
	ds_read_b128 v[196:199], v226 offset:20496
	ds_read_b128 v[200:203], v226 offset:20512
	ds_read_b128 v[204:207], v226 offset:20528
	ds_read_b128 v[208:211], v226 offset:20544
	ds_read_b128 v[212:215], v226 offset:20560
	ds_read_b128 v[216:219], v226 offset:20576
	ds_read_b128 v[220:223], v226 offset:20592
	s_waitcnt lgkmcnt(0)
	v_fmac_f32_e32 v17, v192, v112
	v_fmac_f32_e32 v17, v193, v113
	v_fmac_f32_e32 v17, v194, v114
	v_fmac_f32_e32 v17, v195, v115
	v_fmac_f32_e32 v17, v196, v116
	v_fmac_f32_e32 v17, v197, v117
	v_fmac_f32_e32 v17, v198, v118
	v_fmac_f32_e32 v17, v199, v119
	v_fmac_f32_e32 v17, v200, v120
	v_fmac_f32_e32 v17, v201, v121
	v_fmac_f32_e32 v17, v202, v122
	v_fmac_f32_e32 v17, v203, v123
	v_fmac_f32_e32 v17, v204, v124
	v_fmac_f32_e32 v17, v205, v125
	v_fmac_f32_e32 v17, v206, v126
	v_fmac_f32_e32 v17, v207, v127
	v_fmac_f32_e32 v17, v208, v128
	v_fmac_f32_e32 v17, v209, v129
	v_fmac_f32_e32 v17, v210, v130
	v_fmac_f32_e32 v17, v211, v131
	v_fmac_f32_e32 v17, v212, v132
	v_fmac_f32_e32 v17, v213, v133
	v_fmac_f32_e32 v17, v214, v134
	v_fmac_f32_e32 v17, v215, v135
	v_fmac_f32_e32 v17, v216, v136
	v_fmac_f32_e32 v17, v217, v137
	v_fmac_f32_e32 v17, v218, v138
	v_fmac_f32_e32 v17, v219, v139
	v_fmac_f32_e32 v17, v220, v140
	v_fmac_f32_e32 v17, v221, v141
	v_fmac_f32_e32 v17, v222, v142
	v_fmac_f32_e32 v17, v223, v143
	ds_read_b128 v[192:195], v226 offset:24576
	ds_read_b128 v[196:199], v226 offset:24592
	ds_read_b128 v[200:203], v226 offset:24608
	ds_read_b128 v[204:207], v226 offset:24624
	ds_read_b128 v[208:211], v226 offset:24640
	ds_read_b128 v[212:215], v226 offset:24656
	ds_read_b128 v[216:219], v226 offset:24672
	ds_read_b128 v[220:223], v226 offset:24688
	s_waitcnt lgkmcnt(0)
	v_fmac_f32_e32 v14, v192, v112
	v_fmac_f32_e32 v14, v193, v113
	v_fmac_f32_e32 v14, v194, v114
	v_fmac_f32_e32 v14, v195, v115
	v_fmac_f32_e32 v14, v196, v116
	v_fmac_f32_e32 v14, v197, v117
	v_fmac_f32_e32 v14, v198, v118
	v_fmac_f32_e32 v14, v199, v119
	v_fmac_f32_e32 v14, v200, v120
	v_fmac_f32_e32 v14, v201, v121
	v_fmac_f32_e32 v14, v202, v122
	v_fmac_f32_e32 v14, v203, v123
	v_fmac_f32_e32 v14, v204, v124
	v_fmac_f32_e32 v14, v205, v125
	v_fmac_f32_e32 v14, v206, v126
	v_fmac_f32_e32 v14, v207, v127
	v_fmac_f32_e32 v14, v208, v128
	v_fmac_f32_e32 v14, v209, v129
	v_fmac_f32_e32 v14, v210, v130
	v_fmac_f32_e32 v14, v211, v131
	v_fmac_f32_e32 v14, v212, v132
	v_fmac_f32_e32 v14, v213, v133
	v_fmac_f32_e32 v14, v214, v134
	v_fmac_f32_e32 v14, v215, v135
	v_fmac_f32_e32 v14, v216, v136
	v_fmac_f32_e32 v14, v217, v137
	v_fmac_f32_e32 v14, v218, v138
	v_fmac_f32_e32 v14, v219, v139
	v_fmac_f32_e32 v14, v220, v140
	v_fmac_f32_e32 v14, v221, v141
	v_fmac_f32_e32 v14, v222, v142
	v_fmac_f32_e32 v14, v223, v143
	ds_read_b128 v[192:195], v226 offset:28672
	ds_read_b128 v[196:199], v226 offset:28688
	ds_read_b128 v[200:203], v226 offset:28704
	ds_read_b128 v[204:207], v226 offset:28720
	ds_read_b128 v[208:211], v226 offset:28736
	ds_read_b128 v[212:215], v226 offset:28752
	ds_read_b128 v[216:219], v226 offset:28768
	ds_read_b128 v[220:223], v226 offset:28784
	s_waitcnt lgkmcnt(0)
	v_fmac_f32_e32 v15, v192, v112
	v_fmac_f32_e32 v15, v193, v113
	v_fmac_f32_e32 v15, v194, v114
	v_fmac_f32_e32 v15, v195, v115
	v_fmac_f32_e32 v15, v196, v116
	v_fmac_f32_e32 v15, v197, v117
	v_fmac_f32_e32 v15, v198, v118
	v_fmac_f32_e32 v15, v199, v119
	v_fmac_f32_e32 v15, v200, v120
	v_fmac_f32_e32 v15, v201, v121
	v_fmac_f32_e32 v15, v202, v122
	v_fmac_f32_e32 v15, v203, v123
	v_fmac_f32_e32 v15, v204, v124
	v_fmac_f32_e32 v15, v205, v125
	v_fmac_f32_e32 v15, v206, v126
	v_fmac_f32_e32 v15, v207, v127
	v_fmac_f32_e32 v15, v208, v128
	v_fmac_f32_e32 v15, v209, v129
	v_fmac_f32_e32 v15, v210, v130
	v_fmac_f32_e32 v15, v211, v131
	v_fmac_f32_e32 v15, v212, v132
	v_fmac_f32_e32 v15, v213, v133
	v_fmac_f32_e32 v15, v214, v134
	v_fmac_f32_e32 v15, v215, v135
	v_fmac_f32_e32 v15, v216, v136
	v_fmac_f32_e32 v15, v217, v137
	v_fmac_f32_e32 v15, v218, v138
	v_fmac_f32_e32 v15, v219, v139
	v_fmac_f32_e32 v15, v220, v140
	v_fmac_f32_e32 v15, v221, v141
	v_fmac_f32_e32 v15, v222, v142
	v_fmac_f32_e32 v15, v223, v143
	s_add_i32 s8, s8, 32
	s_lshl_b32 s9, s8, 2
	s_add_i32 s9, s15, s9
	v_mov_b32_e32 v226, s9
	ds_read_b128 v[192:195], v226
	ds_read_b128 v[196:199], v226 offset:16
	ds_read_b128 v[200:203], v226 offset:32
	ds_read_b128 v[204:207], v226 offset:48
	ds_read_b128 v[208:211], v226 offset:64
	ds_read_b128 v[212:215], v226 offset:80
	ds_read_b128 v[216:219], v226 offset:96
	ds_read_b128 v[220:223], v226 offset:112
	s_waitcnt lgkmcnt(0)
	s_waitcnt vmcnt(31)
	v_fmac_f32_e32 v26, v192, v82
	s_waitcnt vmcnt(30)
	v_fmac_f32_e32 v26, v193, v83
	s_waitcnt vmcnt(29)
	v_fmac_f32_e32 v26, v194, v84
	s_waitcnt vmcnt(28)
	v_fmac_f32_e32 v26, v195, v85
	s_waitcnt vmcnt(27)
	v_fmac_f32_e32 v26, v196, v86
	s_waitcnt vmcnt(26)
	v_fmac_f32_e32 v26, v197, v87
	s_waitcnt vmcnt(25)
	v_fmac_f32_e32 v26, v198, v88
	s_waitcnt vmcnt(24)
	v_fmac_f32_e32 v26, v199, v89
	s_waitcnt vmcnt(23)
	v_fmac_f32_e32 v26, v200, v90
	s_waitcnt vmcnt(22)
	v_fmac_f32_e32 v26, v201, v91
	s_waitcnt vmcnt(21)
	v_fmac_f32_e32 v26, v202, v92
	s_waitcnt vmcnt(20)
	v_fmac_f32_e32 v26, v203, v93
	s_waitcnt vmcnt(19)
	v_fmac_f32_e32 v26, v204, v94
	s_waitcnt vmcnt(18)
	v_fmac_f32_e32 v26, v205, v95
	s_waitcnt vmcnt(17)
	v_fmac_f32_e32 v26, v206, v96
	s_waitcnt vmcnt(16)
	v_fmac_f32_e32 v26, v207, v97
	s_waitcnt vmcnt(15)
	v_fmac_f32_e32 v26, v208, v98
	s_waitcnt vmcnt(14)
	v_fmac_f32_e32 v26, v209, v99
	s_waitcnt vmcnt(13)
	v_fmac_f32_e32 v26, v210, v100
	s_waitcnt vmcnt(12)
	v_fmac_f32_e32 v26, v211, v101
	s_waitcnt vmcnt(11)
	v_fmac_f32_e32 v26, v212, v102
	s_waitcnt vmcnt(10)
	v_fmac_f32_e32 v26, v213, v103
	s_waitcnt vmcnt(9)
	v_fmac_f32_e32 v26, v214, v104
	s_waitcnt vmcnt(8)
	v_fmac_f32_e32 v26, v215, v105
	s_waitcnt vmcnt(7)
	v_fmac_f32_e32 v26, v216, v106
	s_waitcnt vmcnt(6)
	v_fmac_f32_e32 v26, v217, v107
	s_waitcnt vmcnt(5)
	v_fmac_f32_e32 v26, v218, v108
	s_waitcnt vmcnt(4)
	v_fmac_f32_e32 v26, v219, v109
	s_waitcnt vmcnt(3)
	v_fmac_f32_e32 v26, v220, v110
	s_waitcnt vmcnt(2)
	v_fmac_f32_e32 v26, v221, v111
	s_waitcnt vmcnt(1)
	v_fmac_f32_e32 v26, v222, v144
	s_waitcnt vmcnt(0)
	v_fmac_f32_e32 v26, v223, v145
	ds_read_b128 v[192:195], v226 offset:4096
	ds_read_b128 v[196:199], v226 offset:4112
	ds_read_b128 v[200:203], v226 offset:4128
	ds_read_b128 v[204:207], v226 offset:4144
	ds_read_b128 v[208:211], v226 offset:4160
	ds_read_b128 v[212:215], v226 offset:4176
	ds_read_b128 v[216:219], v226 offset:4192
	ds_read_b128 v[220:223], v226 offset:4208
	s_waitcnt lgkmcnt(0)
	v_fmac_f32_e32 v27, v192, v82
	v_fmac_f32_e32 v27, v193, v83
	v_fmac_f32_e32 v27, v194, v84
	v_fmac_f32_e32 v27, v195, v85
	v_fmac_f32_e32 v27, v196, v86
	v_fmac_f32_e32 v27, v197, v87
	v_fmac_f32_e32 v27, v198, v88
	v_fmac_f32_e32 v27, v199, v89
	v_fmac_f32_e32 v27, v200, v90
	v_fmac_f32_e32 v27, v201, v91
	v_fmac_f32_e32 v27, v202, v92
	v_fmac_f32_e32 v27, v203, v93
	v_fmac_f32_e32 v27, v204, v94
	v_fmac_f32_e32 v27, v205, v95
	v_fmac_f32_e32 v27, v206, v96
	v_fmac_f32_e32 v27, v207, v97
	v_fmac_f32_e32 v27, v208, v98
	v_fmac_f32_e32 v27, v209, v99
	v_fmac_f32_e32 v27, v210, v100
	v_fmac_f32_e32 v27, v211, v101
	v_fmac_f32_e32 v27, v212, v102
	v_fmac_f32_e32 v27, v213, v103
	v_fmac_f32_e32 v27, v214, v104
	v_fmac_f32_e32 v27, v215, v105
	v_fmac_f32_e32 v27, v216, v106
	v_fmac_f32_e32 v27, v217, v107
	v_fmac_f32_e32 v27, v218, v108
	v_fmac_f32_e32 v27, v219, v109
	v_fmac_f32_e32 v27, v220, v110
	v_fmac_f32_e32 v27, v221, v111
	v_fmac_f32_e32 v27, v222, v144
	v_fmac_f32_e32 v27, v223, v145
	ds_read_b128 v[192:195], v226 offset:8192
	ds_read_b128 v[196:199], v226 offset:8208
	ds_read_b128 v[200:203], v226 offset:8224
	ds_read_b128 v[204:207], v226 offset:8240
	ds_read_b128 v[208:211], v226 offset:8256
	ds_read_b128 v[212:215], v226 offset:8272
	ds_read_b128 v[216:219], v226 offset:8288
	ds_read_b128 v[220:223], v226 offset:8304
	s_waitcnt lgkmcnt(0)
	v_fmac_f32_e32 v42, v192, v82
	v_fmac_f32_e32 v42, v193, v83
	v_fmac_f32_e32 v42, v194, v84
	v_fmac_f32_e32 v42, v195, v85
	v_fmac_f32_e32 v42, v196, v86
	v_fmac_f32_e32 v42, v197, v87
	v_fmac_f32_e32 v42, v198, v88
	v_fmac_f32_e32 v42, v199, v89
	v_fmac_f32_e32 v42, v200, v90
	v_fmac_f32_e32 v42, v201, v91
	v_fmac_f32_e32 v42, v202, v92
	v_fmac_f32_e32 v42, v203, v93
	v_fmac_f32_e32 v42, v204, v94
	v_fmac_f32_e32 v42, v205, v95
	v_fmac_f32_e32 v42, v206, v96
	v_fmac_f32_e32 v42, v207, v97
	v_fmac_f32_e32 v42, v208, v98
	v_fmac_f32_e32 v42, v209, v99
	v_fmac_f32_e32 v42, v210, v100
	v_fmac_f32_e32 v42, v211, v101
	v_fmac_f32_e32 v42, v212, v102
	v_fmac_f32_e32 v42, v213, v103
	v_fmac_f32_e32 v42, v214, v104
	v_fmac_f32_e32 v42, v215, v105
	v_fmac_f32_e32 v42, v216, v106
	v_fmac_f32_e32 v42, v217, v107
	v_fmac_f32_e32 v42, v218, v108
	v_fmac_f32_e32 v42, v219, v109
	v_fmac_f32_e32 v42, v220, v110
	v_fmac_f32_e32 v42, v221, v111
	v_fmac_f32_e32 v42, v222, v144
	v_fmac_f32_e32 v42, v223, v145
	ds_read_b128 v[192:195], v226 offset:12288
	ds_read_b128 v[196:199], v226 offset:12304
	ds_read_b128 v[200:203], v226 offset:12320
	ds_read_b128 v[204:207], v226 offset:12336
	ds_read_b128 v[208:211], v226 offset:12352
	ds_read_b128 v[212:215], v226 offset:12368
	ds_read_b128 v[216:219], v226 offset:12384
	ds_read_b128 v[220:223], v226 offset:12400
	s_waitcnt lgkmcnt(0)
	v_fmac_f32_e32 v43, v192, v82
	v_fmac_f32_e32 v43, v193, v83
	v_fmac_f32_e32 v43, v194, v84
	v_fmac_f32_e32 v43, v195, v85
	v_fmac_f32_e32 v43, v196, v86
	v_fmac_f32_e32 v43, v197, v87
	v_fmac_f32_e32 v43, v198, v88
	v_fmac_f32_e32 v43, v199, v89
	v_fmac_f32_e32 v43, v200, v90
	v_fmac_f32_e32 v43, v201, v91
	v_fmac_f32_e32 v43, v202, v92
	v_fmac_f32_e32 v43, v203, v93
	v_fmac_f32_e32 v43, v204, v94
	v_fmac_f32_e32 v43, v205, v95
	v_fmac_f32_e32 v43, v206, v96
	v_fmac_f32_e32 v43, v207, v97
	v_fmac_f32_e32 v43, v208, v98
	v_fmac_f32_e32 v43, v209, v99
	v_fmac_f32_e32 v43, v210, v100
	v_fmac_f32_e32 v43, v211, v101
	v_fmac_f32_e32 v43, v212, v102
	v_fmac_f32_e32 v43, v213, v103
	v_fmac_f32_e32 v43, v214, v104
	v_fmac_f32_e32 v43, v215, v105
	v_fmac_f32_e32 v43, v216, v106
	v_fmac_f32_e32 v43, v217, v107
	v_fmac_f32_e32 v43, v218, v108
	v_fmac_f32_e32 v43, v219, v109
	v_fmac_f32_e32 v43, v220, v110
	v_fmac_f32_e32 v43, v221, v111
	v_fmac_f32_e32 v43, v222, v144
	v_fmac_f32_e32 v43, v223, v145
	ds_read_b128 v[192:195], v226 offset:16384
	ds_read_b128 v[196:199], v226 offset:16400
	ds_read_b128 v[200:203], v226 offset:16416
	ds_read_b128 v[204:207], v226 offset:16432
	ds_read_b128 v[208:211], v226 offset:16448
	ds_read_b128 v[212:215], v226 offset:16464
	ds_read_b128 v[216:219], v226 offset:16480
	ds_read_b128 v[220:223], v226 offset:16496
	s_waitcnt lgkmcnt(0)
	v_fmac_f32_e32 v16, v192, v82
	v_fmac_f32_e32 v16, v193, v83
	v_fmac_f32_e32 v16, v194, v84
	v_fmac_f32_e32 v16, v195, v85
	v_fmac_f32_e32 v16, v196, v86
	v_fmac_f32_e32 v16, v197, v87
	v_fmac_f32_e32 v16, v198, v88
	v_fmac_f32_e32 v16, v199, v89
	v_fmac_f32_e32 v16, v200, v90
	v_fmac_f32_e32 v16, v201, v91
	v_fmac_f32_e32 v16, v202, v92
	v_fmac_f32_e32 v16, v203, v93
	v_fmac_f32_e32 v16, v204, v94
	v_fmac_f32_e32 v16, v205, v95
	v_fmac_f32_e32 v16, v206, v96
	v_fmac_f32_e32 v16, v207, v97
	v_fmac_f32_e32 v16, v208, v98
	v_fmac_f32_e32 v16, v209, v99
	v_fmac_f32_e32 v16, v210, v100
	v_fmac_f32_e32 v16, v211, v101
	v_fmac_f32_e32 v16, v212, v102
	v_fmac_f32_e32 v16, v213, v103
	v_fmac_f32_e32 v16, v214, v104
	v_fmac_f32_e32 v16, v215, v105
	v_fmac_f32_e32 v16, v216, v106
	v_fmac_f32_e32 v16, v217, v107
	v_fmac_f32_e32 v16, v218, v108
	v_fmac_f32_e32 v16, v219, v109
	v_fmac_f32_e32 v16, v220, v110
	v_fmac_f32_e32 v16, v221, v111
	v_fmac_f32_e32 v16, v222, v144
	v_fmac_f32_e32 v16, v223, v145
	ds_read_b128 v[192:195], v226 offset:20480
	ds_read_b128 v[196:199], v226 offset:20496
	ds_read_b128 v[200:203], v226 offset:20512
	ds_read_b128 v[204:207], v226 offset:20528
	ds_read_b128 v[208:211], v226 offset:20544
	ds_read_b128 v[212:215], v226 offset:20560
	ds_read_b128 v[216:219], v226 offset:20576
	ds_read_b128 v[220:223], v226 offset:20592
	s_waitcnt lgkmcnt(0)
	v_fmac_f32_e32 v17, v192, v82
	v_fmac_f32_e32 v17, v193, v83
	v_fmac_f32_e32 v17, v194, v84
	v_fmac_f32_e32 v17, v195, v85
	v_fmac_f32_e32 v17, v196, v86
	v_fmac_f32_e32 v17, v197, v87
	v_fmac_f32_e32 v17, v198, v88
	v_fmac_f32_e32 v17, v199, v89
	v_fmac_f32_e32 v17, v200, v90
	v_fmac_f32_e32 v17, v201, v91
	v_fmac_f32_e32 v17, v202, v92
	v_fmac_f32_e32 v17, v203, v93
	v_fmac_f32_e32 v17, v204, v94
	v_fmac_f32_e32 v17, v205, v95
	v_fmac_f32_e32 v17, v206, v96
	v_fmac_f32_e32 v17, v207, v97
	v_fmac_f32_e32 v17, v208, v98
	v_fmac_f32_e32 v17, v209, v99
	v_fmac_f32_e32 v17, v210, v100
	v_fmac_f32_e32 v17, v211, v101
	v_fmac_f32_e32 v17, v212, v102
	v_fmac_f32_e32 v17, v213, v103
	v_fmac_f32_e32 v17, v214, v104
	v_fmac_f32_e32 v17, v215, v105
	v_fmac_f32_e32 v17, v216, v106
	v_fmac_f32_e32 v17, v217, v107
	v_fmac_f32_e32 v17, v218, v108
	v_fmac_f32_e32 v17, v219, v109
	v_fmac_f32_e32 v17, v220, v110
	v_fmac_f32_e32 v17, v221, v111
	v_fmac_f32_e32 v17, v222, v144
	v_fmac_f32_e32 v17, v223, v145
	ds_read_b128 v[192:195], v226 offset:24576
	ds_read_b128 v[196:199], v226 offset:24592
	ds_read_b128 v[200:203], v226 offset:24608
	ds_read_b128 v[204:207], v226 offset:24624
	ds_read_b128 v[208:211], v226 offset:24640
	ds_read_b128 v[212:215], v226 offset:24656
	ds_read_b128 v[216:219], v226 offset:24672
	ds_read_b128 v[220:223], v226 offset:24688
	s_waitcnt lgkmcnt(0)
	v_fmac_f32_e32 v14, v192, v82
	v_fmac_f32_e32 v14, v193, v83
	v_fmac_f32_e32 v14, v194, v84
	v_fmac_f32_e32 v14, v195, v85
	v_fmac_f32_e32 v14, v196, v86
	v_fmac_f32_e32 v14, v197, v87
	v_fmac_f32_e32 v14, v198, v88
	v_fmac_f32_e32 v14, v199, v89
	v_fmac_f32_e32 v14, v200, v90
	v_fmac_f32_e32 v14, v201, v91
	v_fmac_f32_e32 v14, v202, v92
	v_fmac_f32_e32 v14, v203, v93
	v_fmac_f32_e32 v14, v204, v94
	v_fmac_f32_e32 v14, v205, v95
	v_fmac_f32_e32 v14, v206, v96
	v_fmac_f32_e32 v14, v207, v97
	v_fmac_f32_e32 v14, v208, v98
	v_fmac_f32_e32 v14, v209, v99
	v_fmac_f32_e32 v14, v210, v100
	v_fmac_f32_e32 v14, v211, v101
	v_fmac_f32_e32 v14, v212, v102
	v_fmac_f32_e32 v14, v213, v103
	v_fmac_f32_e32 v14, v214, v104
	v_fmac_f32_e32 v14, v215, v105
	v_fmac_f32_e32 v14, v216, v106
	v_fmac_f32_e32 v14, v217, v107
	v_fmac_f32_e32 v14, v218, v108
	v_fmac_f32_e32 v14, v219, v109
	v_fmac_f32_e32 v14, v220, v110
	v_fmac_f32_e32 v14, v221, v111
	v_fmac_f32_e32 v14, v222, v144
	v_fmac_f32_e32 v14, v223, v145
	ds_read_b128 v[192:195], v226 offset:28672
	ds_read_b128 v[196:199], v226 offset:28688
	ds_read_b128 v[200:203], v226 offset:28704
	ds_read_b128 v[204:207], v226 offset:28720
	ds_read_b128 v[208:211], v226 offset:28736
	ds_read_b128 v[212:215], v226 offset:28752
	ds_read_b128 v[216:219], v226 offset:28768
	ds_read_b128 v[220:223], v226 offset:28784
	s_waitcnt lgkmcnt(0)
	v_fmac_f32_e32 v15, v192, v82
	v_fmac_f32_e32 v15, v193, v83
	v_fmac_f32_e32 v15, v194, v84
	v_fmac_f32_e32 v15, v195, v85
	v_fmac_f32_e32 v15, v196, v86
	v_fmac_f32_e32 v15, v197, v87
	v_fmac_f32_e32 v15, v198, v88
	v_fmac_f32_e32 v15, v199, v89
	v_fmac_f32_e32 v15, v200, v90
	v_fmac_f32_e32 v15, v201, v91
	v_fmac_f32_e32 v15, v202, v92
	v_fmac_f32_e32 v15, v203, v93
	v_fmac_f32_e32 v15, v204, v94
	v_fmac_f32_e32 v15, v205, v95
	v_fmac_f32_e32 v15, v206, v96
	v_fmac_f32_e32 v15, v207, v97
	v_fmac_f32_e32 v15, v208, v98
	v_fmac_f32_e32 v15, v209, v99
	v_fmac_f32_e32 v15, v210, v100
	v_fmac_f32_e32 v15, v211, v101
	v_fmac_f32_e32 v15, v212, v102
	v_fmac_f32_e32 v15, v213, v103
	v_fmac_f32_e32 v15, v214, v104
	v_fmac_f32_e32 v15, v215, v105
	v_fmac_f32_e32 v15, v216, v106
	v_fmac_f32_e32 v15, v217, v107
	v_fmac_f32_e32 v15, v218, v108
	v_fmac_f32_e32 v15, v219, v109
	v_fmac_f32_e32 v15, v220, v110
	v_fmac_f32_e32 v15, v221, v111
	v_fmac_f32_e32 v15, v222, v144
	v_fmac_f32_e32 v15, v223, v145
	s_add_i32 s8, s8, 32
	v_add_u32_e32 v2, s16, v47
	ds_write2st64_b32 v2, v26, v27 offset0:128 offset1:129
	ds_write2st64_b32 v2, v42, v43 offset0:130 offset1:131
	ds_write2st64_b32 v2, v16, v17 offset0:132 offset1:133
	ds_write2st64_b32 v2, v14, v15 offset0:134 offset1:135
	v_add_u32_e32 v2, s4, v46
	v_ashrrev_i32_e32 v3, 31, v2
	v_lshl_add_u64 v[2:3], v[2:3], 2, s[10:11]
	s_waitcnt lgkmcnt(0)
	s_barrier
	global_load_dword v12, v[2:3], off
	ds_read2st64_b32 v[4:5], v80 offset0:128 offset1:136
	ds_read2st64_b32 v[6:7], v80 offset0:144 offset1:152
	ds_read2st64_b32 v[8:9], v80 offset0:160 offset1:168
	ds_read2st64_b32 v[10:11], v80 offset0:176 offset1:184
	s_add_u32 s6, s46, s6
	s_waitcnt lgkmcnt(3)
	v_add_f32_e32 v4, 0, v4
	v_add_f32_e32 v4, v4, v5
	s_waitcnt lgkmcnt(2)
	v_add_f32_e32 v4, v4, v6
	v_add_f32_e32 v4, v4, v7
	s_waitcnt lgkmcnt(1)
	v_add_f32_e32 v4, v4, v8
	v_mad_i64_i32 v[2:3], s[8:9], s12, v146, 0
	s_addc_u32 s7, s47, s7
	v_add_f32_e32 v4, v4, v9
	v_lshl_add_u64 v[2:3], v[2:3], 2, s[6:7]
	s_waitcnt lgkmcnt(0)
	v_add_f32_e32 v4, v4, v10
	s_add_i32 s60, s60, s62
	v_lshl_add_u64 v[2:3], s[4:5], 2, v[2:3]
	v_add_f32_e32 v4, v4, v11
	s_cmpk_gt_i32 s60, 0x19f
	v_lshl_add_u64 v[2:3], v[2:3], 0, v[0:1]
	s_waitcnt vmcnt(0)
	v_add_f32_e32 v4, v4, v12
	global_store_dword v[2:3], v4, off
	s_barrier
	s_cbranch_scc0 .LBB0_1582
